# phase2 pool: each wave takes 8 consecutive tokens, 23 window rows loaded once into registers (XCD owns a sequence)
# speedup vs baseline: 1.0040x; 1.0040x over previous
.LBB0_253:
	s_cmp_lt_i32 s92, 3
	s_cselect_b64 s[0:1], -1, 0
	s_cmp_gt_i32 s93, 2
	s_cselect_b64 s[4:5], -1, 0
	s_and_b64 s[0:1], s[0:1], s[4:5]
	s_andn2_b64 vcc, exec, s[0:1]
	s_cbranch_vccnz .LBB0_489
	s_cmpk_gt_i32 s2, 0x107f
	s_cbranch_scc1 .LBB0_271
	v_lshlrev_b32_e32 v2, 3, v218
	v_bfe_u32 v1, v218, 4, 2
	v_and_b32_e32 v2, 0x78, v2
	v_lshl_or_b32 v2, v1, 7, v2
	v_and_b32_e32 v0, 63, v218
	v_lshlrev_b32_e32 v8, 1, v2
	v_mov_b32_e32 v9, 0
	v_lshl_add_u64 v[10:11], s[90:91], 0, v[8:9]
	v_lshlrev_b32_e32 v8, 4, v0
	v_lshl_add_u64 v[12:13], s[88:89], 0, v[8:9]
	v_lshlrev_b32_e32 v8, 2, v2
	v_lshlrev_b32_e64 v38, v1, 2
	v_lshl_add_u64 v[0:1], s[72:73], 0, v[8:9]
	s_mov_b64 s[0:1], 0x7010
	v_lshl_add_u64 v[14:15], v[0:1], 0, s[0:1]
	s_movk_i32 s0, 0xfc00
	s_mov_b32 s1, -1
	v_lshl_add_u64 v[16:17], v[10:11], 0, s[0:1]
	s_movk_i32 s3, 0x1200
	s_mov_b32 s8, s2
	s_cmpk_lg_i32 s94, 0x200
	s_cbranch_scc1 .Lpool_skip
	v_and_b32_e32 v172, 63, v218
	v_lshrrev_b32_e32 v173, 4, v172
	v_and_b32_e32 v174, 15, v172
	v_lshlrev_b32_e32 v175, 4, v172
	v_lshlrev_b32_e32 v174, 3, v174
	v_lshl_add_u32 v172, v173, 7, v174
	v_lshlrev_b32_e32 v172, 1, v172
	v_add_u32_e32 v172, 0xe00, v172
	v_lshlrev_b32_e64 v204, v173, 2
	v_lshrrev_b32_e32 v174, 6, v218
	s_lshr_b32 s21, s2, 3
	s_lshl_b32 s21, s21, 2
	v_readfirstlane_b32 s23, v174
	s_and_b32 s20, s2, 7
	s_lshl_b32 s20, s20, 11
	s_add_i32 s21, s21, s23
	s_lshl_b32 s22, s21, 3
	s_add_i32 s20, s20, s22
	s_add_i32 s21, s20, -15
	s_max_i32 s21, s21, 0
	s_mul_i32 s21, s21, 0x1200
	s_add_u32 s24, s90, s21
	s_addc_u32 s25, s91, 0
	global_load_dwordx4 v[44:47], v172, s[24:25]
	s_add_i32 s21, s20, -14
	s_max_i32 s21, s21, 0
	s_mul_i32 s21, s21, 0x1200
	s_add_u32 s24, s90, s21
	s_addc_u32 s25, s91, 0
	global_load_dwordx4 v[48:51], v172, s[24:25]
	s_add_i32 s21, s20, -13
	s_max_i32 s21, s21, 0
	s_mul_i32 s21, s21, 0x1200
	s_add_u32 s24, s90, s21
	s_addc_u32 s25, s91, 0
	global_load_dwordx4 v[52:55], v172, s[24:25]
	s_add_i32 s21, s20, -12
	s_max_i32 s21, s21, 0
	s_mul_i32 s21, s21, 0x1200
	s_add_u32 s24, s90, s21
	s_addc_u32 s25, s91, 0
	global_load_dwordx4 v[56:59], v172, s[24:25]
	s_add_i32 s21, s20, -11
	s_max_i32 s21, s21, 0
	s_mul_i32 s21, s21, 0x1200
	s_add_u32 s24, s90, s21
	s_addc_u32 s25, s91, 0
	global_load_dwordx4 v[60:63], v172, s[24:25]
	s_add_i32 s21, s20, -10
	s_max_i32 s21, s21, 0
	s_mul_i32 s21, s21, 0x1200
	s_add_u32 s24, s90, s21
	s_addc_u32 s25, s91, 0
	global_load_dwordx4 v[64:67], v172, s[24:25]
	s_add_i32 s21, s20, -9
	s_max_i32 s21, s21, 0
	s_mul_i32 s21, s21, 0x1200
	s_add_u32 s24, s90, s21
	s_addc_u32 s25, s91, 0
	global_load_dwordx4 v[68:71], v172, s[24:25]
	s_add_i32 s21, s20, -8
	s_max_i32 s21, s21, 0
	s_mul_i32 s21, s21, 0x1200
	s_add_u32 s24, s90, s21
	s_addc_u32 s25, s91, 0
	global_load_dwordx4 v[72:75], v172, s[24:25]
	s_add_i32 s21, s20, -7
	s_max_i32 s21, s21, 0
	s_mul_i32 s21, s21, 0x1200
	s_add_u32 s24, s90, s21
	s_addc_u32 s25, s91, 0
	global_load_dwordx4 v[76:79], v172, s[24:25]
	s_add_i32 s21, s20, -6
	s_max_i32 s21, s21, 0
	s_mul_i32 s21, s21, 0x1200
	s_add_u32 s24, s90, s21
	s_addc_u32 s25, s91, 0
	global_load_dwordx4 v[80:83], v172, s[24:25]
	s_add_i32 s21, s20, -5
	s_max_i32 s21, s21, 0
	s_mul_i32 s21, s21, 0x1200
	s_add_u32 s24, s90, s21
	s_addc_u32 s25, s91, 0
	global_load_dwordx4 v[84:87], v172, s[24:25]
	s_add_i32 s21, s20, -4
	s_max_i32 s21, s21, 0
	s_mul_i32 s21, s21, 0x1200
	s_add_u32 s24, s90, s21
	s_addc_u32 s25, s91, 0
	global_load_dwordx4 v[88:91], v172, s[24:25]
	s_add_i32 s21, s20, -3
	s_max_i32 s21, s21, 0
	s_mul_i32 s21, s21, 0x1200
	s_add_u32 s24, s90, s21
	s_addc_u32 s25, s91, 0
	global_load_dwordx4 v[92:95], v172, s[24:25]
	s_add_i32 s21, s20, -2
	s_max_i32 s21, s21, 0
	s_mul_i32 s21, s21, 0x1200
	s_add_u32 s24, s90, s21
	s_addc_u32 s25, s91, 0
	global_load_dwordx4 v[96:99], v172, s[24:25]
	s_add_i32 s21, s20, -1
	s_max_i32 s21, s21, 0
	s_mul_i32 s21, s21, 0x1200
	s_add_u32 s24, s90, s21
	s_addc_u32 s25, s91, 0
	global_load_dwordx4 v[100:103], v172, s[24:25]
	s_mov_b32 s21, s20
	s_max_i32 s21, s21, 0
	s_mul_i32 s21, s21, 0x1200
	s_add_u32 s24, s90, s21
	s_addc_u32 s25, s91, 0
	global_load_dwordx4 v[104:107], v172, s[24:25]
	s_add_i32 s21, s20, 1
	s_max_i32 s21, s21, 0
	s_mul_i32 s21, s21, 0x1200
	s_add_u32 s24, s90, s21
	s_addc_u32 s25, s91, 0
	global_load_dwordx4 v[108:111], v172, s[24:25]
	s_add_i32 s21, s20, 2
	s_max_i32 s21, s21, 0
	s_mul_i32 s21, s21, 0x1200
	s_add_u32 s24, s90, s21
	s_addc_u32 s25, s91, 0
	global_load_dwordx4 v[112:115], v172, s[24:25]
	s_add_i32 s21, s20, 3
	s_max_i32 s21, s21, 0
	s_mul_i32 s21, s21, 0x1200
	s_add_u32 s24, s90, s21
	s_addc_u32 s25, s91, 0
	global_load_dwordx4 v[116:119], v172, s[24:25]
	s_add_i32 s21, s20, 4
	s_max_i32 s21, s21, 0
	s_mul_i32 s21, s21, 0x1200
	s_add_u32 s24, s90, s21
	s_addc_u32 s25, s91, 0
	global_load_dwordx4 v[120:123], v172, s[24:25]
	s_add_i32 s21, s20, 5
	s_max_i32 s21, s21, 0
	s_mul_i32 s21, s21, 0x1200
	s_add_u32 s24, s90, s21
	s_addc_u32 s25, s91, 0
	global_load_dwordx4 v[124:127], v172, s[24:25]
	s_add_i32 s21, s20, 6
	s_max_i32 s21, s21, 0
	s_mul_i32 s21, s21, 0x1200
	s_add_u32 s24, s90, s21
	s_addc_u32 s25, s91, 0
	global_load_dwordx4 v[128:131], v172, s[24:25]
	s_add_i32 s21, s20, 7
	s_max_i32 s21, s21, 0
	s_mul_i32 s21, s21, 0x1200
	s_add_u32 s24, s90, s21
	s_addc_u32 s25, s91, 0
	global_load_dwordx4 v[132:135], v172, s[24:25]
	s_mov_b64 s[26:27], exec
	s_add_i32 s21, s22, 1
	v_min_u32_e32 v173, s21, v204
	v_cvt_f32_u32_e32 v0, v173
	v_div_scale_f32 v1, s[0:1], v0, v0, 1.0
	v_rcp_f32_e32 v2, v1
	v_div_scale_f32 v3, vcc, 1.0, v0, 1.0
	v_fma_f32 v4, -v1, v2, 1.0
	v_fmac_f32_e32 v2, v4, v2
	v_mul_f32_e32 v4, v3, v2
	v_fma_f32 v5, -v1, v4, v3
	v_fmac_f32_e32 v4, v5, v2
	v_fma_f32 v1, -v1, v4, v3
	v_div_fmas_f32 v1, v1, v2, v4
	v_div_fixup_f32 v174, v1, v0, 1.0
	s_waitcnt vmcnt(7)
	v_lshlrev_b32_e32 v176, 16, v104
	v_and_b32_e32 v177, 0xffff0000, v104
	v_lshlrev_b32_e32 v178, 16, v105
	v_and_b32_e32 v179, 0xffff0000, v105
	v_lshlrev_b32_e32 v180, 16, v106
	v_and_b32_e32 v181, 0xffff0000, v106
	v_lshlrev_b32_e32 v182, 16, v107
	v_and_b32_e32 v183, 0xffff0000, v107
	v_mov_b32_e32 v184, v176
	v_mov_b32_e32 v185, v177
	v_mov_b32_e32 v186, v178
	v_mov_b32_e32 v187, v179
	v_mov_b32_e32 v188, v180
	v_mov_b32_e32 v189, v181
	v_mov_b32_e32 v190, v182
	v_mov_b32_e32 v191, v183
	v_cmp_lt_u32_e32 vcc, 1, v173
	s_and_b64 exec, exec, vcc
	v_lshlrev_b32_e32 v192, 16, v100
	v_and_b32_e32 v193, 0xffff0000, v100
	v_lshlrev_b32_e32 v194, 16, v101
	v_and_b32_e32 v195, 0xffff0000, v101
	v_lshlrev_b32_e32 v196, 16, v102
	v_and_b32_e32 v197, 0xffff0000, v102
	v_lshlrev_b32_e32 v198, 16, v103
	v_and_b32_e32 v199, 0xffff0000, v103
	v_pk_add_f32 v[184:185], v[184:185], v[192:193]
	v_pk_add_f32 v[186:187], v[186:187], v[194:195]
	v_pk_add_f32 v[188:189], v[188:189], v[196:197]
	v_pk_add_f32 v[190:191], v[190:191], v[198:199]
	v_cmp_lt_u32_e32 vcc, 2, v173
	s_and_b64 exec, exec, vcc
	v_lshlrev_b32_e32 v192, 16, v96
	v_and_b32_e32 v193, 0xffff0000, v96
	v_lshlrev_b32_e32 v194, 16, v97
	v_and_b32_e32 v195, 0xffff0000, v97
	v_lshlrev_b32_e32 v196, 16, v98
	v_and_b32_e32 v197, 0xffff0000, v98
	v_lshlrev_b32_e32 v198, 16, v99
	v_and_b32_e32 v199, 0xffff0000, v99
	v_pk_add_f32 v[184:185], v[184:185], v[192:193]
	v_pk_add_f32 v[186:187], v[186:187], v[194:195]
	v_pk_add_f32 v[188:189], v[188:189], v[196:197]
	v_pk_add_f32 v[190:191], v[190:191], v[198:199]
	v_cmp_lt_u32_e32 vcc, 3, v173
	s_and_b64 exec, exec, vcc
	v_lshlrev_b32_e32 v192, 16, v92
	v_and_b32_e32 v193, 0xffff0000, v92
	v_lshlrev_b32_e32 v194, 16, v93
	v_and_b32_e32 v195, 0xffff0000, v93
	v_lshlrev_b32_e32 v196, 16, v94
	v_and_b32_e32 v197, 0xffff0000, v94
	v_lshlrev_b32_e32 v198, 16, v95
	v_and_b32_e32 v199, 0xffff0000, v95
	v_pk_add_f32 v[184:185], v[184:185], v[192:193]
	v_pk_add_f32 v[186:187], v[186:187], v[194:195]
	v_pk_add_f32 v[188:189], v[188:189], v[196:197]
	v_pk_add_f32 v[190:191], v[190:191], v[198:199]
	v_cmp_lt_u32_e32 vcc, 4, v173
	s_and_b64 exec, exec, vcc
	v_lshlrev_b32_e32 v192, 16, v88
	v_and_b32_e32 v193, 0xffff0000, v88
	v_lshlrev_b32_e32 v194, 16, v89
	v_and_b32_e32 v195, 0xffff0000, v89
	v_lshlrev_b32_e32 v196, 16, v90
	v_and_b32_e32 v197, 0xffff0000, v90
	v_lshlrev_b32_e32 v198, 16, v91
	v_and_b32_e32 v199, 0xffff0000, v91
	v_pk_add_f32 v[184:185], v[184:185], v[192:193]
	v_pk_add_f32 v[186:187], v[186:187], v[194:195]
	v_pk_add_f32 v[188:189], v[188:189], v[196:197]
	v_pk_add_f32 v[190:191], v[190:191], v[198:199]
	v_cmp_lt_u32_e32 vcc, 5, v173
	s_and_b64 exec, exec, vcc
	v_lshlrev_b32_e32 v192, 16, v84
	v_and_b32_e32 v193, 0xffff0000, v84
	v_lshlrev_b32_e32 v194, 16, v85
	v_and_b32_e32 v195, 0xffff0000, v85
	v_lshlrev_b32_e32 v196, 16, v86
	v_and_b32_e32 v197, 0xffff0000, v86
	v_lshlrev_b32_e32 v198, 16, v87
	v_and_b32_e32 v199, 0xffff0000, v87
	v_pk_add_f32 v[184:185], v[184:185], v[192:193]
	v_pk_add_f32 v[186:187], v[186:187], v[194:195]
	v_pk_add_f32 v[188:189], v[188:189], v[196:197]
	v_pk_add_f32 v[190:191], v[190:191], v[198:199]
	v_cmp_lt_u32_e32 vcc, 6, v173
	s_and_b64 exec, exec, vcc
	v_lshlrev_b32_e32 v192, 16, v80
	v_and_b32_e32 v193, 0xffff0000, v80
	v_lshlrev_b32_e32 v194, 16, v81
	v_and_b32_e32 v195, 0xffff0000, v81
	v_lshlrev_b32_e32 v196, 16, v82
	v_and_b32_e32 v197, 0xffff0000, v82
	v_lshlrev_b32_e32 v198, 16, v83
	v_and_b32_e32 v199, 0xffff0000, v83
	v_pk_add_f32 v[184:185], v[184:185], v[192:193]
	v_pk_add_f32 v[186:187], v[186:187], v[194:195]
	v_pk_add_f32 v[188:189], v[188:189], v[196:197]
	v_pk_add_f32 v[190:191], v[190:191], v[198:199]
	v_cmp_lt_u32_e32 vcc, 7, v173
	s_and_b64 exec, exec, vcc
	v_lshlrev_b32_e32 v192, 16, v76
	v_and_b32_e32 v193, 0xffff0000, v76
	v_lshlrev_b32_e32 v194, 16, v77
	v_and_b32_e32 v195, 0xffff0000, v77
	v_lshlrev_b32_e32 v196, 16, v78
	v_and_b32_e32 v197, 0xffff0000, v78
	v_lshlrev_b32_e32 v198, 16, v79
	v_and_b32_e32 v199, 0xffff0000, v79
	v_pk_add_f32 v[184:185], v[184:185], v[192:193]
	v_pk_add_f32 v[186:187], v[186:187], v[194:195]
	v_pk_add_f32 v[188:189], v[188:189], v[196:197]
	v_pk_add_f32 v[190:191], v[190:191], v[198:199]
	v_cmp_lt_u32_e32 vcc, 8, v173
	s_and_b64 exec, exec, vcc
	v_lshlrev_b32_e32 v192, 16, v72
	v_and_b32_e32 v193, 0xffff0000, v72
	v_lshlrev_b32_e32 v194, 16, v73
	v_and_b32_e32 v195, 0xffff0000, v73
	v_lshlrev_b32_e32 v196, 16, v74
	v_and_b32_e32 v197, 0xffff0000, v74
	v_lshlrev_b32_e32 v198, 16, v75
	v_and_b32_e32 v199, 0xffff0000, v75
	v_pk_add_f32 v[184:185], v[184:185], v[192:193]
	v_pk_add_f32 v[186:187], v[186:187], v[194:195]
	v_pk_add_f32 v[188:189], v[188:189], v[196:197]
	v_pk_add_f32 v[190:191], v[190:191], v[198:199]
	v_cmp_lt_u32_e32 vcc, 9, v173
	s_and_b64 exec, exec, vcc
	v_lshlrev_b32_e32 v192, 16, v68
	v_and_b32_e32 v193, 0xffff0000, v68
	v_lshlrev_b32_e32 v194, 16, v69
	v_and_b32_e32 v195, 0xffff0000, v69
	v_lshlrev_b32_e32 v196, 16, v70
	v_and_b32_e32 v197, 0xffff0000, v70
	v_lshlrev_b32_e32 v198, 16, v71
	v_and_b32_e32 v199, 0xffff0000, v71
	v_pk_add_f32 v[184:185], v[184:185], v[192:193]
	v_pk_add_f32 v[186:187], v[186:187], v[194:195]
	v_pk_add_f32 v[188:189], v[188:189], v[196:197]
	v_pk_add_f32 v[190:191], v[190:191], v[198:199]
	v_cmp_lt_u32_e32 vcc, 10, v173
	s_and_b64 exec, exec, vcc
	v_lshlrev_b32_e32 v192, 16, v64
	v_and_b32_e32 v193, 0xffff0000, v64
	v_lshlrev_b32_e32 v194, 16, v65
	v_and_b32_e32 v195, 0xffff0000, v65
	v_lshlrev_b32_e32 v196, 16, v66
	v_and_b32_e32 v197, 0xffff0000, v66
	v_lshlrev_b32_e32 v198, 16, v67
	v_and_b32_e32 v199, 0xffff0000, v67
	v_pk_add_f32 v[184:185], v[184:185], v[192:193]
	v_pk_add_f32 v[186:187], v[186:187], v[194:195]
	v_pk_add_f32 v[188:189], v[188:189], v[196:197]
	v_pk_add_f32 v[190:191], v[190:191], v[198:199]
	v_cmp_lt_u32_e32 vcc, 11, v173
	s_and_b64 exec, exec, vcc
	v_lshlrev_b32_e32 v192, 16, v60
	v_and_b32_e32 v193, 0xffff0000, v60
	v_lshlrev_b32_e32 v194, 16, v61
	v_and_b32_e32 v195, 0xffff0000, v61
	v_lshlrev_b32_e32 v196, 16, v62
	v_and_b32_e32 v197, 0xffff0000, v62
	v_lshlrev_b32_e32 v198, 16, v63
	v_and_b32_e32 v199, 0xffff0000, v63
	v_pk_add_f32 v[184:185], v[184:185], v[192:193]
	v_pk_add_f32 v[186:187], v[186:187], v[194:195]
	v_pk_add_f32 v[188:189], v[188:189], v[196:197]
	v_pk_add_f32 v[190:191], v[190:191], v[198:199]
	v_cmp_lt_u32_e32 vcc, 12, v173
	s_and_b64 exec, exec, vcc
	v_lshlrev_b32_e32 v192, 16, v56
	v_and_b32_e32 v193, 0xffff0000, v56
	v_lshlrev_b32_e32 v194, 16, v57
	v_and_b32_e32 v195, 0xffff0000, v57
	v_lshlrev_b32_e32 v196, 16, v58
	v_and_b32_e32 v197, 0xffff0000, v58
	v_lshlrev_b32_e32 v198, 16, v59
	v_and_b32_e32 v199, 0xffff0000, v59
	v_pk_add_f32 v[184:185], v[184:185], v[192:193]
	v_pk_add_f32 v[186:187], v[186:187], v[194:195]
	v_pk_add_f32 v[188:189], v[188:189], v[196:197]
	v_pk_add_f32 v[190:191], v[190:191], v[198:199]
	v_cmp_lt_u32_e32 vcc, 13, v173
	s_and_b64 exec, exec, vcc
	v_lshlrev_b32_e32 v192, 16, v52
	v_and_b32_e32 v193, 0xffff0000, v52
	v_lshlrev_b32_e32 v194, 16, v53
	v_and_b32_e32 v195, 0xffff0000, v53
	v_lshlrev_b32_e32 v196, 16, v54
	v_and_b32_e32 v197, 0xffff0000, v54
	v_lshlrev_b32_e32 v198, 16, v55
	v_and_b32_e32 v199, 0xffff0000, v55
	v_pk_add_f32 v[184:185], v[184:185], v[192:193]
	v_pk_add_f32 v[186:187], v[186:187], v[194:195]
	v_pk_add_f32 v[188:189], v[188:189], v[196:197]
	v_pk_add_f32 v[190:191], v[190:191], v[198:199]
	v_cmp_lt_u32_e32 vcc, 14, v173
	s_and_b64 exec, exec, vcc
	v_lshlrev_b32_e32 v192, 16, v48
	v_and_b32_e32 v193, 0xffff0000, v48
	v_lshlrev_b32_e32 v194, 16, v49
	v_and_b32_e32 v195, 0xffff0000, v49
	v_lshlrev_b32_e32 v196, 16, v50
	v_and_b32_e32 v197, 0xffff0000, v50
	v_lshlrev_b32_e32 v198, 16, v51
	v_and_b32_e32 v199, 0xffff0000, v51
	v_pk_add_f32 v[184:185], v[184:185], v[192:193]
	v_pk_add_f32 v[186:187], v[186:187], v[194:195]
	v_pk_add_f32 v[188:189], v[188:189], v[196:197]
	v_pk_add_f32 v[190:191], v[190:191], v[198:199]
	v_cmp_lt_u32_e32 vcc, 15, v173
	s_and_b64 exec, exec, vcc
	v_lshlrev_b32_e32 v192, 16, v44
	v_and_b32_e32 v193, 0xffff0000, v44
	v_lshlrev_b32_e32 v194, 16, v45
	v_and_b32_e32 v195, 0xffff0000, v45
	v_lshlrev_b32_e32 v196, 16, v46
	v_and_b32_e32 v197, 0xffff0000, v46
	v_lshlrev_b32_e32 v198, 16, v47
	v_and_b32_e32 v199, 0xffff0000, v47
	v_pk_add_f32 v[184:185], v[184:185], v[192:193]
	v_pk_add_f32 v[186:187], v[186:187], v[194:195]
	v_pk_add_f32 v[188:189], v[188:189], v[196:197]
	v_pk_add_f32 v[190:191], v[190:191], v[198:199]
	s_mov_b64 exec, s[26:27]
	v_pk_fma_f32 v[184:185], v[184:185], v[174:175], v[176:177] op_sel_hi:[1,0,1] neg_lo:[0,0,1] neg_hi:[0,0,1]
	v_pk_fma_f32 v[186:187], v[186:187], v[174:175], v[178:179] op_sel_hi:[1,0,1] neg_lo:[0,0,1] neg_hi:[0,0,1]
	v_pk_fma_f32 v[188:189], v[188:189], v[174:175], v[180:181] op_sel_hi:[1,0,1] neg_lo:[0,0,1] neg_hi:[0,0,1]
	v_pk_fma_f32 v[190:191], v[190:191], v[174:175], v[182:183] op_sel_hi:[1,0,1] neg_lo:[0,0,1] neg_hi:[0,0,1]
	v_cvt_pk_bf16_f32 v200, v184, v185
	v_cvt_pk_bf16_f32 v201, v186, v187
	v_cvt_pk_bf16_f32 v202, v188, v189
	v_cvt_pk_bf16_f32 v203, v190, v191
	s_add_i32 s21, s20, 0
	s_lshl_b32 s21, s21, 10
	s_add_u32 s24, s88, s21
	s_addc_u32 s25, s89, 0
	global_store_dwordx4 v175, v[200:203], s[24:25]
	s_add_i32 s21, s22, 2
	v_min_u32_e32 v173, s21, v204
	v_cvt_f32_u32_e32 v0, v173
	v_div_scale_f32 v1, s[0:1], v0, v0, 1.0
	v_rcp_f32_e32 v2, v1
	v_div_scale_f32 v3, vcc, 1.0, v0, 1.0
	v_fma_f32 v4, -v1, v2, 1.0
	v_fmac_f32_e32 v2, v4, v2
	v_mul_f32_e32 v4, v3, v2
	v_fma_f32 v5, -v1, v4, v3
	v_fmac_f32_e32 v4, v5, v2
	v_fma_f32 v1, -v1, v4, v3
	v_div_fmas_f32 v1, v1, v2, v4
	v_div_fixup_f32 v174, v1, v0, 1.0
	s_waitcnt vmcnt(7)
	v_lshlrev_b32_e32 v176, 16, v108
	v_and_b32_e32 v177, 0xffff0000, v108
	v_lshlrev_b32_e32 v178, 16, v109
	v_and_b32_e32 v179, 0xffff0000, v109
	v_lshlrev_b32_e32 v180, 16, v110
	v_and_b32_e32 v181, 0xffff0000, v110
	v_lshlrev_b32_e32 v182, 16, v111
	v_and_b32_e32 v183, 0xffff0000, v111
	v_mov_b32_e32 v184, v176
	v_mov_b32_e32 v185, v177
	v_mov_b32_e32 v186, v178
	v_mov_b32_e32 v187, v179
	v_mov_b32_e32 v188, v180
	v_mov_b32_e32 v189, v181
	v_mov_b32_e32 v190, v182
	v_mov_b32_e32 v191, v183
	v_cmp_lt_u32_e32 vcc, 1, v173
	s_and_b64 exec, exec, vcc
	v_lshlrev_b32_e32 v192, 16, v104
	v_and_b32_e32 v193, 0xffff0000, v104
	v_lshlrev_b32_e32 v194, 16, v105
	v_and_b32_e32 v195, 0xffff0000, v105
	v_lshlrev_b32_e32 v196, 16, v106
	v_and_b32_e32 v197, 0xffff0000, v106
	v_lshlrev_b32_e32 v198, 16, v107
	v_and_b32_e32 v199, 0xffff0000, v107
	v_pk_add_f32 v[184:185], v[184:185], v[192:193]
	v_pk_add_f32 v[186:187], v[186:187], v[194:195]
	v_pk_add_f32 v[188:189], v[188:189], v[196:197]
	v_pk_add_f32 v[190:191], v[190:191], v[198:199]
	v_cmp_lt_u32_e32 vcc, 2, v173
	s_and_b64 exec, exec, vcc
	v_lshlrev_b32_e32 v192, 16, v100
	v_and_b32_e32 v193, 0xffff0000, v100
	v_lshlrev_b32_e32 v194, 16, v101
	v_and_b32_e32 v195, 0xffff0000, v101
	v_lshlrev_b32_e32 v196, 16, v102
	v_and_b32_e32 v197, 0xffff0000, v102
	v_lshlrev_b32_e32 v198, 16, v103
	v_and_b32_e32 v199, 0xffff0000, v103
	v_pk_add_f32 v[184:185], v[184:185], v[192:193]
	v_pk_add_f32 v[186:187], v[186:187], v[194:195]
	v_pk_add_f32 v[188:189], v[188:189], v[196:197]
	v_pk_add_f32 v[190:191], v[190:191], v[198:199]
	v_cmp_lt_u32_e32 vcc, 3, v173
	s_and_b64 exec, exec, vcc
	v_lshlrev_b32_e32 v192, 16, v96
	v_and_b32_e32 v193, 0xffff0000, v96
	v_lshlrev_b32_e32 v194, 16, v97
	v_and_b32_e32 v195, 0xffff0000, v97
	v_lshlrev_b32_e32 v196, 16, v98
	v_and_b32_e32 v197, 0xffff0000, v98
	v_lshlrev_b32_e32 v198, 16, v99
	v_and_b32_e32 v199, 0xffff0000, v99
	v_pk_add_f32 v[184:185], v[184:185], v[192:193]
	v_pk_add_f32 v[186:187], v[186:187], v[194:195]
	v_pk_add_f32 v[188:189], v[188:189], v[196:197]
	v_pk_add_f32 v[190:191], v[190:191], v[198:199]
	v_cmp_lt_u32_e32 vcc, 4, v173
	s_and_b64 exec, exec, vcc
	v_lshlrev_b32_e32 v192, 16, v92
	v_and_b32_e32 v193, 0xffff0000, v92
	v_lshlrev_b32_e32 v194, 16, v93
	v_and_b32_e32 v195, 0xffff0000, v93
	v_lshlrev_b32_e32 v196, 16, v94
	v_and_b32_e32 v197, 0xffff0000, v94
	v_lshlrev_b32_e32 v198, 16, v95
	v_and_b32_e32 v199, 0xffff0000, v95
	v_pk_add_f32 v[184:185], v[184:185], v[192:193]
	v_pk_add_f32 v[186:187], v[186:187], v[194:195]
	v_pk_add_f32 v[188:189], v[188:189], v[196:197]
	v_pk_add_f32 v[190:191], v[190:191], v[198:199]
	v_cmp_lt_u32_e32 vcc, 5, v173
	s_and_b64 exec, exec, vcc
	v_lshlrev_b32_e32 v192, 16, v88
	v_and_b32_e32 v193, 0xffff0000, v88
	v_lshlrev_b32_e32 v194, 16, v89
	v_and_b32_e32 v195, 0xffff0000, v89
	v_lshlrev_b32_e32 v196, 16, v90
	v_and_b32_e32 v197, 0xffff0000, v90
	v_lshlrev_b32_e32 v198, 16, v91
	v_and_b32_e32 v199, 0xffff0000, v91
	v_pk_add_f32 v[184:185], v[184:185], v[192:193]
	v_pk_add_f32 v[186:187], v[186:187], v[194:195]
	v_pk_add_f32 v[188:189], v[188:189], v[196:197]
	v_pk_add_f32 v[190:191], v[190:191], v[198:199]
	v_cmp_lt_u32_e32 vcc, 6, v173
	s_and_b64 exec, exec, vcc
	v_lshlrev_b32_e32 v192, 16, v84
	v_and_b32_e32 v193, 0xffff0000, v84
	v_lshlrev_b32_e32 v194, 16, v85
	v_and_b32_e32 v195, 0xffff0000, v85
	v_lshlrev_b32_e32 v196, 16, v86
	v_and_b32_e32 v197, 0xffff0000, v86
	v_lshlrev_b32_e32 v198, 16, v87
	v_and_b32_e32 v199, 0xffff0000, v87
	v_pk_add_f32 v[184:185], v[184:185], v[192:193]
	v_pk_add_f32 v[186:187], v[186:187], v[194:195]
	v_pk_add_f32 v[188:189], v[188:189], v[196:197]
	v_pk_add_f32 v[190:191], v[190:191], v[198:199]
	v_cmp_lt_u32_e32 vcc, 7, v173
	s_and_b64 exec, exec, vcc
	v_lshlrev_b32_e32 v192, 16, v80
	v_and_b32_e32 v193, 0xffff0000, v80
	v_lshlrev_b32_e32 v194, 16, v81
	v_and_b32_e32 v195, 0xffff0000, v81
	v_lshlrev_b32_e32 v196, 16, v82
	v_and_b32_e32 v197, 0xffff0000, v82
	v_lshlrev_b32_e32 v198, 16, v83
	v_and_b32_e32 v199, 0xffff0000, v83
	v_pk_add_f32 v[184:185], v[184:185], v[192:193]
	v_pk_add_f32 v[186:187], v[186:187], v[194:195]
	v_pk_add_f32 v[188:189], v[188:189], v[196:197]
	v_pk_add_f32 v[190:191], v[190:191], v[198:199]
	v_cmp_lt_u32_e32 vcc, 8, v173
	s_and_b64 exec, exec, vcc
	v_lshlrev_b32_e32 v192, 16, v76
	v_and_b32_e32 v193, 0xffff0000, v76
	v_lshlrev_b32_e32 v194, 16, v77
	v_and_b32_e32 v195, 0xffff0000, v77
	v_lshlrev_b32_e32 v196, 16, v78
	v_and_b32_e32 v197, 0xffff0000, v78
	v_lshlrev_b32_e32 v198, 16, v79
	v_and_b32_e32 v199, 0xffff0000, v79
	v_pk_add_f32 v[184:185], v[184:185], v[192:193]
	v_pk_add_f32 v[186:187], v[186:187], v[194:195]
	v_pk_add_f32 v[188:189], v[188:189], v[196:197]
	v_pk_add_f32 v[190:191], v[190:191], v[198:199]
	v_cmp_lt_u32_e32 vcc, 9, v173
	s_and_b64 exec, exec, vcc
	v_lshlrev_b32_e32 v192, 16, v72
	v_and_b32_e32 v193, 0xffff0000, v72
	v_lshlrev_b32_e32 v194, 16, v73
	v_and_b32_e32 v195, 0xffff0000, v73
	v_lshlrev_b32_e32 v196, 16, v74
	v_and_b32_e32 v197, 0xffff0000, v74
	v_lshlrev_b32_e32 v198, 16, v75
	v_and_b32_e32 v199, 0xffff0000, v75
	v_pk_add_f32 v[184:185], v[184:185], v[192:193]
	v_pk_add_f32 v[186:187], v[186:187], v[194:195]
	v_pk_add_f32 v[188:189], v[188:189], v[196:197]
	v_pk_add_f32 v[190:191], v[190:191], v[198:199]
	v_cmp_lt_u32_e32 vcc, 10, v173
	s_and_b64 exec, exec, vcc
	v_lshlrev_b32_e32 v192, 16, v68
	v_and_b32_e32 v193, 0xffff0000, v68
	v_lshlrev_b32_e32 v194, 16, v69
	v_and_b32_e32 v195, 0xffff0000, v69
	v_lshlrev_b32_e32 v196, 16, v70
	v_and_b32_e32 v197, 0xffff0000, v70
	v_lshlrev_b32_e32 v198, 16, v71
	v_and_b32_e32 v199, 0xffff0000, v71
	v_pk_add_f32 v[184:185], v[184:185], v[192:193]
	v_pk_add_f32 v[186:187], v[186:187], v[194:195]
	v_pk_add_f32 v[188:189], v[188:189], v[196:197]
	v_pk_add_f32 v[190:191], v[190:191], v[198:199]
	v_cmp_lt_u32_e32 vcc, 11, v173
	s_and_b64 exec, exec, vcc
	v_lshlrev_b32_e32 v192, 16, v64
	v_and_b32_e32 v193, 0xffff0000, v64
	v_lshlrev_b32_e32 v194, 16, v65
	v_and_b32_e32 v195, 0xffff0000, v65
	v_lshlrev_b32_e32 v196, 16, v66
	v_and_b32_e32 v197, 0xffff0000, v66
	v_lshlrev_b32_e32 v198, 16, v67
	v_and_b32_e32 v199, 0xffff0000, v67
	v_pk_add_f32 v[184:185], v[184:185], v[192:193]
	v_pk_add_f32 v[186:187], v[186:187], v[194:195]
	v_pk_add_f32 v[188:189], v[188:189], v[196:197]
	v_pk_add_f32 v[190:191], v[190:191], v[198:199]
	v_cmp_lt_u32_e32 vcc, 12, v173
	s_and_b64 exec, exec, vcc
	v_lshlrev_b32_e32 v192, 16, v60
	v_and_b32_e32 v193, 0xffff0000, v60
	v_lshlrev_b32_e32 v194, 16, v61
	v_and_b32_e32 v195, 0xffff0000, v61
	v_lshlrev_b32_e32 v196, 16, v62
	v_and_b32_e32 v197, 0xffff0000, v62
	v_lshlrev_b32_e32 v198, 16, v63
	v_and_b32_e32 v199, 0xffff0000, v63
	v_pk_add_f32 v[184:185], v[184:185], v[192:193]
	v_pk_add_f32 v[186:187], v[186:187], v[194:195]
	v_pk_add_f32 v[188:189], v[188:189], v[196:197]
	v_pk_add_f32 v[190:191], v[190:191], v[198:199]
	v_cmp_lt_u32_e32 vcc, 13, v173
	s_and_b64 exec, exec, vcc
	v_lshlrev_b32_e32 v192, 16, v56
	v_and_b32_e32 v193, 0xffff0000, v56
	v_lshlrev_b32_e32 v194, 16, v57
	v_and_b32_e32 v195, 0xffff0000, v57
	v_lshlrev_b32_e32 v196, 16, v58
	v_and_b32_e32 v197, 0xffff0000, v58
	v_lshlrev_b32_e32 v198, 16, v59
	v_and_b32_e32 v199, 0xffff0000, v59
	v_pk_add_f32 v[184:185], v[184:185], v[192:193]
	v_pk_add_f32 v[186:187], v[186:187], v[194:195]
	v_pk_add_f32 v[188:189], v[188:189], v[196:197]
	v_pk_add_f32 v[190:191], v[190:191], v[198:199]
	v_cmp_lt_u32_e32 vcc, 14, v173
	s_and_b64 exec, exec, vcc
	v_lshlrev_b32_e32 v192, 16, v52
	v_and_b32_e32 v193, 0xffff0000, v52
	v_lshlrev_b32_e32 v194, 16, v53
	v_and_b32_e32 v195, 0xffff0000, v53
	v_lshlrev_b32_e32 v196, 16, v54
	v_and_b32_e32 v197, 0xffff0000, v54
	v_lshlrev_b32_e32 v198, 16, v55
	v_and_b32_e32 v199, 0xffff0000, v55
	v_pk_add_f32 v[184:185], v[184:185], v[192:193]
	v_pk_add_f32 v[186:187], v[186:187], v[194:195]
	v_pk_add_f32 v[188:189], v[188:189], v[196:197]
	v_pk_add_f32 v[190:191], v[190:191], v[198:199]
	v_cmp_lt_u32_e32 vcc, 15, v173
	s_and_b64 exec, exec, vcc
	v_lshlrev_b32_e32 v192, 16, v48
	v_and_b32_e32 v193, 0xffff0000, v48
	v_lshlrev_b32_e32 v194, 16, v49
	v_and_b32_e32 v195, 0xffff0000, v49
	v_lshlrev_b32_e32 v196, 16, v50
	v_and_b32_e32 v197, 0xffff0000, v50
	v_lshlrev_b32_e32 v198, 16, v51
	v_and_b32_e32 v199, 0xffff0000, v51
	v_pk_add_f32 v[184:185], v[184:185], v[192:193]
	v_pk_add_f32 v[186:187], v[186:187], v[194:195]
	v_pk_add_f32 v[188:189], v[188:189], v[196:197]
	v_pk_add_f32 v[190:191], v[190:191], v[198:199]
	s_mov_b64 exec, s[26:27]
	v_pk_fma_f32 v[184:185], v[184:185], v[174:175], v[176:177] op_sel_hi:[1,0,1] neg_lo:[0,0,1] neg_hi:[0,0,1]
	v_pk_fma_f32 v[186:187], v[186:187], v[174:175], v[178:179] op_sel_hi:[1,0,1] neg_lo:[0,0,1] neg_hi:[0,0,1]
	v_pk_fma_f32 v[188:189], v[188:189], v[174:175], v[180:181] op_sel_hi:[1,0,1] neg_lo:[0,0,1] neg_hi:[0,0,1]
	v_pk_fma_f32 v[190:191], v[190:191], v[174:175], v[182:183] op_sel_hi:[1,0,1] neg_lo:[0,0,1] neg_hi:[0,0,1]
	v_cvt_pk_bf16_f32 v200, v184, v185
	v_cvt_pk_bf16_f32 v201, v186, v187
	v_cvt_pk_bf16_f32 v202, v188, v189
	v_cvt_pk_bf16_f32 v203, v190, v191
	s_add_i32 s21, s20, 1
	s_lshl_b32 s21, s21, 10
	s_add_u32 s24, s88, s21
	s_addc_u32 s25, s89, 0
	global_store_dwordx4 v175, v[200:203], s[24:25]
	s_add_i32 s21, s22, 3
	v_min_u32_e32 v173, s21, v204
	v_cvt_f32_u32_e32 v0, v173
	v_div_scale_f32 v1, s[0:1], v0, v0, 1.0
	v_rcp_f32_e32 v2, v1
	v_div_scale_f32 v3, vcc, 1.0, v0, 1.0
	v_fma_f32 v4, -v1, v2, 1.0
	v_fmac_f32_e32 v2, v4, v2
	v_mul_f32_e32 v4, v3, v2
	v_fma_f32 v5, -v1, v4, v3
	v_fmac_f32_e32 v4, v5, v2
	v_fma_f32 v1, -v1, v4, v3
	v_div_fmas_f32 v1, v1, v2, v4
	v_div_fixup_f32 v174, v1, v0, 1.0
	s_waitcnt vmcnt(7)
	v_lshlrev_b32_e32 v176, 16, v112
	v_and_b32_e32 v177, 0xffff0000, v112
	v_lshlrev_b32_e32 v178, 16, v113
	v_and_b32_e32 v179, 0xffff0000, v113
	v_lshlrev_b32_e32 v180, 16, v114
	v_and_b32_e32 v181, 0xffff0000, v114
	v_lshlrev_b32_e32 v182, 16, v115
	v_and_b32_e32 v183, 0xffff0000, v115
	v_mov_b32_e32 v184, v176
	v_mov_b32_e32 v185, v177
	v_mov_b32_e32 v186, v178
	v_mov_b32_e32 v187, v179
	v_mov_b32_e32 v188, v180
	v_mov_b32_e32 v189, v181
	v_mov_b32_e32 v190, v182
	v_mov_b32_e32 v191, v183
	v_cmp_lt_u32_e32 vcc, 1, v173
	s_and_b64 exec, exec, vcc
	v_lshlrev_b32_e32 v192, 16, v108
	v_and_b32_e32 v193, 0xffff0000, v108
	v_lshlrev_b32_e32 v194, 16, v109
	v_and_b32_e32 v195, 0xffff0000, v109
	v_lshlrev_b32_e32 v196, 16, v110
	v_and_b32_e32 v197, 0xffff0000, v110
	v_lshlrev_b32_e32 v198, 16, v111
	v_and_b32_e32 v199, 0xffff0000, v111
	v_pk_add_f32 v[184:185], v[184:185], v[192:193]
	v_pk_add_f32 v[186:187], v[186:187], v[194:195]
	v_pk_add_f32 v[188:189], v[188:189], v[196:197]
	v_pk_add_f32 v[190:191], v[190:191], v[198:199]
	v_cmp_lt_u32_e32 vcc, 2, v173
	s_and_b64 exec, exec, vcc
	v_lshlrev_b32_e32 v192, 16, v104
	v_and_b32_e32 v193, 0xffff0000, v104
	v_lshlrev_b32_e32 v194, 16, v105
	v_and_b32_e32 v195, 0xffff0000, v105
	v_lshlrev_b32_e32 v196, 16, v106
	v_and_b32_e32 v197, 0xffff0000, v106
	v_lshlrev_b32_e32 v198, 16, v107
	v_and_b32_e32 v199, 0xffff0000, v107
	v_pk_add_f32 v[184:185], v[184:185], v[192:193]
	v_pk_add_f32 v[186:187], v[186:187], v[194:195]
	v_pk_add_f32 v[188:189], v[188:189], v[196:197]
	v_pk_add_f32 v[190:191], v[190:191], v[198:199]
	v_cmp_lt_u32_e32 vcc, 3, v173
	s_and_b64 exec, exec, vcc
	v_lshlrev_b32_e32 v192, 16, v100
	v_and_b32_e32 v193, 0xffff0000, v100
	v_lshlrev_b32_e32 v194, 16, v101
	v_and_b32_e32 v195, 0xffff0000, v101
	v_lshlrev_b32_e32 v196, 16, v102
	v_and_b32_e32 v197, 0xffff0000, v102
	v_lshlrev_b32_e32 v198, 16, v103
	v_and_b32_e32 v199, 0xffff0000, v103
	v_pk_add_f32 v[184:185], v[184:185], v[192:193]
	v_pk_add_f32 v[186:187], v[186:187], v[194:195]
	v_pk_add_f32 v[188:189], v[188:189], v[196:197]
	v_pk_add_f32 v[190:191], v[190:191], v[198:199]
	v_cmp_lt_u32_e32 vcc, 4, v173
	s_and_b64 exec, exec, vcc
	v_lshlrev_b32_e32 v192, 16, v96
	v_and_b32_e32 v193, 0xffff0000, v96
	v_lshlrev_b32_e32 v194, 16, v97
	v_and_b32_e32 v195, 0xffff0000, v97
	v_lshlrev_b32_e32 v196, 16, v98
	v_and_b32_e32 v197, 0xffff0000, v98
	v_lshlrev_b32_e32 v198, 16, v99
	v_and_b32_e32 v199, 0xffff0000, v99
	v_pk_add_f32 v[184:185], v[184:185], v[192:193]
	v_pk_add_f32 v[186:187], v[186:187], v[194:195]
	v_pk_add_f32 v[188:189], v[188:189], v[196:197]
	v_pk_add_f32 v[190:191], v[190:191], v[198:199]
	v_cmp_lt_u32_e32 vcc, 5, v173
	s_and_b64 exec, exec, vcc
	v_lshlrev_b32_e32 v192, 16, v92
	v_and_b32_e32 v193, 0xffff0000, v92
	v_lshlrev_b32_e32 v194, 16, v93
	v_and_b32_e32 v195, 0xffff0000, v93
	v_lshlrev_b32_e32 v196, 16, v94
	v_and_b32_e32 v197, 0xffff0000, v94
	v_lshlrev_b32_e32 v198, 16, v95
	v_and_b32_e32 v199, 0xffff0000, v95
	v_pk_add_f32 v[184:185], v[184:185], v[192:193]
	v_pk_add_f32 v[186:187], v[186:187], v[194:195]
	v_pk_add_f32 v[188:189], v[188:189], v[196:197]
	v_pk_add_f32 v[190:191], v[190:191], v[198:199]
	v_cmp_lt_u32_e32 vcc, 6, v173
	s_and_b64 exec, exec, vcc
	v_lshlrev_b32_e32 v192, 16, v88
	v_and_b32_e32 v193, 0xffff0000, v88
	v_lshlrev_b32_e32 v194, 16, v89
	v_and_b32_e32 v195, 0xffff0000, v89
	v_lshlrev_b32_e32 v196, 16, v90
	v_and_b32_e32 v197, 0xffff0000, v90
	v_lshlrev_b32_e32 v198, 16, v91
	v_and_b32_e32 v199, 0xffff0000, v91
	v_pk_add_f32 v[184:185], v[184:185], v[192:193]
	v_pk_add_f32 v[186:187], v[186:187], v[194:195]
	v_pk_add_f32 v[188:189], v[188:189], v[196:197]
	v_pk_add_f32 v[190:191], v[190:191], v[198:199]
	v_cmp_lt_u32_e32 vcc, 7, v173
	s_and_b64 exec, exec, vcc
	v_lshlrev_b32_e32 v192, 16, v84
	v_and_b32_e32 v193, 0xffff0000, v84
	v_lshlrev_b32_e32 v194, 16, v85
	v_and_b32_e32 v195, 0xffff0000, v85
	v_lshlrev_b32_e32 v196, 16, v86
	v_and_b32_e32 v197, 0xffff0000, v86
	v_lshlrev_b32_e32 v198, 16, v87
	v_and_b32_e32 v199, 0xffff0000, v87
	v_pk_add_f32 v[184:185], v[184:185], v[192:193]
	v_pk_add_f32 v[186:187], v[186:187], v[194:195]
	v_pk_add_f32 v[188:189], v[188:189], v[196:197]
	v_pk_add_f32 v[190:191], v[190:191], v[198:199]
	v_cmp_lt_u32_e32 vcc, 8, v173
	s_and_b64 exec, exec, vcc
	v_lshlrev_b32_e32 v192, 16, v80
	v_and_b32_e32 v193, 0xffff0000, v80
	v_lshlrev_b32_e32 v194, 16, v81
	v_and_b32_e32 v195, 0xffff0000, v81
	v_lshlrev_b32_e32 v196, 16, v82
	v_and_b32_e32 v197, 0xffff0000, v82
	v_lshlrev_b32_e32 v198, 16, v83
	v_and_b32_e32 v199, 0xffff0000, v83
	v_pk_add_f32 v[184:185], v[184:185], v[192:193]
	v_pk_add_f32 v[186:187], v[186:187], v[194:195]
	v_pk_add_f32 v[188:189], v[188:189], v[196:197]
	v_pk_add_f32 v[190:191], v[190:191], v[198:199]
	v_cmp_lt_u32_e32 vcc, 9, v173
	s_and_b64 exec, exec, vcc
	v_lshlrev_b32_e32 v192, 16, v76
	v_and_b32_e32 v193, 0xffff0000, v76
	v_lshlrev_b32_e32 v194, 16, v77
	v_and_b32_e32 v195, 0xffff0000, v77
	v_lshlrev_b32_e32 v196, 16, v78
	v_and_b32_e32 v197, 0xffff0000, v78
	v_lshlrev_b32_e32 v198, 16, v79
	v_and_b32_e32 v199, 0xffff0000, v79
	v_pk_add_f32 v[184:185], v[184:185], v[192:193]
	v_pk_add_f32 v[186:187], v[186:187], v[194:195]
	v_pk_add_f32 v[188:189], v[188:189], v[196:197]
	v_pk_add_f32 v[190:191], v[190:191], v[198:199]
	v_cmp_lt_u32_e32 vcc, 10, v173
	s_and_b64 exec, exec, vcc
	v_lshlrev_b32_e32 v192, 16, v72
	v_and_b32_e32 v193, 0xffff0000, v72
	v_lshlrev_b32_e32 v194, 16, v73
	v_and_b32_e32 v195, 0xffff0000, v73
	v_lshlrev_b32_e32 v196, 16, v74
	v_and_b32_e32 v197, 0xffff0000, v74
	v_lshlrev_b32_e32 v198, 16, v75
	v_and_b32_e32 v199, 0xffff0000, v75
	v_pk_add_f32 v[184:185], v[184:185], v[192:193]
	v_pk_add_f32 v[186:187], v[186:187], v[194:195]
	v_pk_add_f32 v[188:189], v[188:189], v[196:197]
	v_pk_add_f32 v[190:191], v[190:191], v[198:199]
	v_cmp_lt_u32_e32 vcc, 11, v173
	s_and_b64 exec, exec, vcc
	v_lshlrev_b32_e32 v192, 16, v68
	v_and_b32_e32 v193, 0xffff0000, v68
	v_lshlrev_b32_e32 v194, 16, v69
	v_and_b32_e32 v195, 0xffff0000, v69
	v_lshlrev_b32_e32 v196, 16, v70
	v_and_b32_e32 v197, 0xffff0000, v70
	v_lshlrev_b32_e32 v198, 16, v71
	v_and_b32_e32 v199, 0xffff0000, v71
	v_pk_add_f32 v[184:185], v[184:185], v[192:193]
	v_pk_add_f32 v[186:187], v[186:187], v[194:195]
	v_pk_add_f32 v[188:189], v[188:189], v[196:197]
	v_pk_add_f32 v[190:191], v[190:191], v[198:199]
	v_cmp_lt_u32_e32 vcc, 12, v173
	s_and_b64 exec, exec, vcc
	v_lshlrev_b32_e32 v192, 16, v64
	v_and_b32_e32 v193, 0xffff0000, v64
	v_lshlrev_b32_e32 v194, 16, v65
	v_and_b32_e32 v195, 0xffff0000, v65
	v_lshlrev_b32_e32 v196, 16, v66
	v_and_b32_e32 v197, 0xffff0000, v66
	v_lshlrev_b32_e32 v198, 16, v67
	v_and_b32_e32 v199, 0xffff0000, v67
	v_pk_add_f32 v[184:185], v[184:185], v[192:193]
	v_pk_add_f32 v[186:187], v[186:187], v[194:195]
	v_pk_add_f32 v[188:189], v[188:189], v[196:197]
	v_pk_add_f32 v[190:191], v[190:191], v[198:199]
	v_cmp_lt_u32_e32 vcc, 13, v173
	s_and_b64 exec, exec, vcc
	v_lshlrev_b32_e32 v192, 16, v60
	v_and_b32_e32 v193, 0xffff0000, v60
	v_lshlrev_b32_e32 v194, 16, v61
	v_and_b32_e32 v195, 0xffff0000, v61
	v_lshlrev_b32_e32 v196, 16, v62
	v_and_b32_e32 v197, 0xffff0000, v62
	v_lshlrev_b32_e32 v198, 16, v63
	v_and_b32_e32 v199, 0xffff0000, v63
	v_pk_add_f32 v[184:185], v[184:185], v[192:193]
	v_pk_add_f32 v[186:187], v[186:187], v[194:195]
	v_pk_add_f32 v[188:189], v[188:189], v[196:197]
	v_pk_add_f32 v[190:191], v[190:191], v[198:199]
	v_cmp_lt_u32_e32 vcc, 14, v173
	s_and_b64 exec, exec, vcc
	v_lshlrev_b32_e32 v192, 16, v56
	v_and_b32_e32 v193, 0xffff0000, v56
	v_lshlrev_b32_e32 v194, 16, v57
	v_and_b32_e32 v195, 0xffff0000, v57
	v_lshlrev_b32_e32 v196, 16, v58
	v_and_b32_e32 v197, 0xffff0000, v58
	v_lshlrev_b32_e32 v198, 16, v59
	v_and_b32_e32 v199, 0xffff0000, v59
	v_pk_add_f32 v[184:185], v[184:185], v[192:193]
	v_pk_add_f32 v[186:187], v[186:187], v[194:195]
	v_pk_add_f32 v[188:189], v[188:189], v[196:197]
	v_pk_add_f32 v[190:191], v[190:191], v[198:199]
	v_cmp_lt_u32_e32 vcc, 15, v173
	s_and_b64 exec, exec, vcc
	v_lshlrev_b32_e32 v192, 16, v52
	v_and_b32_e32 v193, 0xffff0000, v52
	v_lshlrev_b32_e32 v194, 16, v53
	v_and_b32_e32 v195, 0xffff0000, v53
	v_lshlrev_b32_e32 v196, 16, v54
	v_and_b32_e32 v197, 0xffff0000, v54
	v_lshlrev_b32_e32 v198, 16, v55
	v_and_b32_e32 v199, 0xffff0000, v55
	v_pk_add_f32 v[184:185], v[184:185], v[192:193]
	v_pk_add_f32 v[186:187], v[186:187], v[194:195]
	v_pk_add_f32 v[188:189], v[188:189], v[196:197]
	v_pk_add_f32 v[190:191], v[190:191], v[198:199]
	s_mov_b64 exec, s[26:27]
	v_pk_fma_f32 v[184:185], v[184:185], v[174:175], v[176:177] op_sel_hi:[1,0,1] neg_lo:[0,0,1] neg_hi:[0,0,1]
	v_pk_fma_f32 v[186:187], v[186:187], v[174:175], v[178:179] op_sel_hi:[1,0,1] neg_lo:[0,0,1] neg_hi:[0,0,1]
	v_pk_fma_f32 v[188:189], v[188:189], v[174:175], v[180:181] op_sel_hi:[1,0,1] neg_lo:[0,0,1] neg_hi:[0,0,1]
	v_pk_fma_f32 v[190:191], v[190:191], v[174:175], v[182:183] op_sel_hi:[1,0,1] neg_lo:[0,0,1] neg_hi:[0,0,1]
	v_cvt_pk_bf16_f32 v200, v184, v185
	v_cvt_pk_bf16_f32 v201, v186, v187
	v_cvt_pk_bf16_f32 v202, v188, v189
	v_cvt_pk_bf16_f32 v203, v190, v191
	s_add_i32 s21, s20, 2
	s_lshl_b32 s21, s21, 10
	s_add_u32 s24, s88, s21
	s_addc_u32 s25, s89, 0
	global_store_dwordx4 v175, v[200:203], s[24:25]
	s_add_i32 s21, s22, 4
	v_min_u32_e32 v173, s21, v204
	v_cvt_f32_u32_e32 v0, v173
	v_div_scale_f32 v1, s[0:1], v0, v0, 1.0
	v_rcp_f32_e32 v2, v1
	v_div_scale_f32 v3, vcc, 1.0, v0, 1.0
	v_fma_f32 v4, -v1, v2, 1.0
	v_fmac_f32_e32 v2, v4, v2
	v_mul_f32_e32 v4, v3, v2
	v_fma_f32 v5, -v1, v4, v3
	v_fmac_f32_e32 v4, v5, v2
	v_fma_f32 v1, -v1, v4, v3
	v_div_fmas_f32 v1, v1, v2, v4
	v_div_fixup_f32 v174, v1, v0, 1.0
	s_waitcnt vmcnt(7)
	v_lshlrev_b32_e32 v176, 16, v116
	v_and_b32_e32 v177, 0xffff0000, v116
	v_lshlrev_b32_e32 v178, 16, v117
	v_and_b32_e32 v179, 0xffff0000, v117
	v_lshlrev_b32_e32 v180, 16, v118
	v_and_b32_e32 v181, 0xffff0000, v118
	v_lshlrev_b32_e32 v182, 16, v119
	v_and_b32_e32 v183, 0xffff0000, v119
	v_mov_b32_e32 v184, v176
	v_mov_b32_e32 v185, v177
	v_mov_b32_e32 v186, v178
	v_mov_b32_e32 v187, v179
	v_mov_b32_e32 v188, v180
	v_mov_b32_e32 v189, v181
	v_mov_b32_e32 v190, v182
	v_mov_b32_e32 v191, v183
	v_cmp_lt_u32_e32 vcc, 1, v173
	s_and_b64 exec, exec, vcc
	v_lshlrev_b32_e32 v192, 16, v112
	v_and_b32_e32 v193, 0xffff0000, v112
	v_lshlrev_b32_e32 v194, 16, v113
	v_and_b32_e32 v195, 0xffff0000, v113
	v_lshlrev_b32_e32 v196, 16, v114
	v_and_b32_e32 v197, 0xffff0000, v114
	v_lshlrev_b32_e32 v198, 16, v115
	v_and_b32_e32 v199, 0xffff0000, v115
	v_pk_add_f32 v[184:185], v[184:185], v[192:193]
	v_pk_add_f32 v[186:187], v[186:187], v[194:195]
	v_pk_add_f32 v[188:189], v[188:189], v[196:197]
	v_pk_add_f32 v[190:191], v[190:191], v[198:199]
	v_cmp_lt_u32_e32 vcc, 2, v173
	s_and_b64 exec, exec, vcc
	v_lshlrev_b32_e32 v192, 16, v108
	v_and_b32_e32 v193, 0xffff0000, v108
	v_lshlrev_b32_e32 v194, 16, v109
	v_and_b32_e32 v195, 0xffff0000, v109
	v_lshlrev_b32_e32 v196, 16, v110
	v_and_b32_e32 v197, 0xffff0000, v110
	v_lshlrev_b32_e32 v198, 16, v111
	v_and_b32_e32 v199, 0xffff0000, v111
	v_pk_add_f32 v[184:185], v[184:185], v[192:193]
	v_pk_add_f32 v[186:187], v[186:187], v[194:195]
	v_pk_add_f32 v[188:189], v[188:189], v[196:197]
	v_pk_add_f32 v[190:191], v[190:191], v[198:199]
	v_cmp_lt_u32_e32 vcc, 3, v173
	s_and_b64 exec, exec, vcc
	v_lshlrev_b32_e32 v192, 16, v104
	v_and_b32_e32 v193, 0xffff0000, v104
	v_lshlrev_b32_e32 v194, 16, v105
	v_and_b32_e32 v195, 0xffff0000, v105
	v_lshlrev_b32_e32 v196, 16, v106
	v_and_b32_e32 v197, 0xffff0000, v106
	v_lshlrev_b32_e32 v198, 16, v107
	v_and_b32_e32 v199, 0xffff0000, v107
	v_pk_add_f32 v[184:185], v[184:185], v[192:193]
	v_pk_add_f32 v[186:187], v[186:187], v[194:195]
	v_pk_add_f32 v[188:189], v[188:189], v[196:197]
	v_pk_add_f32 v[190:191], v[190:191], v[198:199]
	v_cmp_lt_u32_e32 vcc, 4, v173
	s_and_b64 exec, exec, vcc
	v_lshlrev_b32_e32 v192, 16, v100
	v_and_b32_e32 v193, 0xffff0000, v100
	v_lshlrev_b32_e32 v194, 16, v101
	v_and_b32_e32 v195, 0xffff0000, v101
	v_lshlrev_b32_e32 v196, 16, v102
	v_and_b32_e32 v197, 0xffff0000, v102
	v_lshlrev_b32_e32 v198, 16, v103
	v_and_b32_e32 v199, 0xffff0000, v103
	v_pk_add_f32 v[184:185], v[184:185], v[192:193]
	v_pk_add_f32 v[186:187], v[186:187], v[194:195]
	v_pk_add_f32 v[188:189], v[188:189], v[196:197]
	v_pk_add_f32 v[190:191], v[190:191], v[198:199]
	v_cmp_lt_u32_e32 vcc, 5, v173
	s_and_b64 exec, exec, vcc
	v_lshlrev_b32_e32 v192, 16, v96
	v_and_b32_e32 v193, 0xffff0000, v96
	v_lshlrev_b32_e32 v194, 16, v97
	v_and_b32_e32 v195, 0xffff0000, v97
	v_lshlrev_b32_e32 v196, 16, v98
	v_and_b32_e32 v197, 0xffff0000, v98
	v_lshlrev_b32_e32 v198, 16, v99
	v_and_b32_e32 v199, 0xffff0000, v99
	v_pk_add_f32 v[184:185], v[184:185], v[192:193]
	v_pk_add_f32 v[186:187], v[186:187], v[194:195]
	v_pk_add_f32 v[188:189], v[188:189], v[196:197]
	v_pk_add_f32 v[190:191], v[190:191], v[198:199]
	v_cmp_lt_u32_e32 vcc, 6, v173
	s_and_b64 exec, exec, vcc
	v_lshlrev_b32_e32 v192, 16, v92
	v_and_b32_e32 v193, 0xffff0000, v92
	v_lshlrev_b32_e32 v194, 16, v93
	v_and_b32_e32 v195, 0xffff0000, v93
	v_lshlrev_b32_e32 v196, 16, v94
	v_and_b32_e32 v197, 0xffff0000, v94
	v_lshlrev_b32_e32 v198, 16, v95
	v_and_b32_e32 v199, 0xffff0000, v95
	v_pk_add_f32 v[184:185], v[184:185], v[192:193]
	v_pk_add_f32 v[186:187], v[186:187], v[194:195]
	v_pk_add_f32 v[188:189], v[188:189], v[196:197]
	v_pk_add_f32 v[190:191], v[190:191], v[198:199]
	v_cmp_lt_u32_e32 vcc, 7, v173
	s_and_b64 exec, exec, vcc
	v_lshlrev_b32_e32 v192, 16, v88
	v_and_b32_e32 v193, 0xffff0000, v88
	v_lshlrev_b32_e32 v194, 16, v89
	v_and_b32_e32 v195, 0xffff0000, v89
	v_lshlrev_b32_e32 v196, 16, v90
	v_and_b32_e32 v197, 0xffff0000, v90
	v_lshlrev_b32_e32 v198, 16, v91
	v_and_b32_e32 v199, 0xffff0000, v91
	v_pk_add_f32 v[184:185], v[184:185], v[192:193]
	v_pk_add_f32 v[186:187], v[186:187], v[194:195]
	v_pk_add_f32 v[188:189], v[188:189], v[196:197]
	v_pk_add_f32 v[190:191], v[190:191], v[198:199]
	v_cmp_lt_u32_e32 vcc, 8, v173
	s_and_b64 exec, exec, vcc
	v_lshlrev_b32_e32 v192, 16, v84
	v_and_b32_e32 v193, 0xffff0000, v84
	v_lshlrev_b32_e32 v194, 16, v85
	v_and_b32_e32 v195, 0xffff0000, v85
	v_lshlrev_b32_e32 v196, 16, v86
	v_and_b32_e32 v197, 0xffff0000, v86
	v_lshlrev_b32_e32 v198, 16, v87
	v_and_b32_e32 v199, 0xffff0000, v87
	v_pk_add_f32 v[184:185], v[184:185], v[192:193]
	v_pk_add_f32 v[186:187], v[186:187], v[194:195]
	v_pk_add_f32 v[188:189], v[188:189], v[196:197]
	v_pk_add_f32 v[190:191], v[190:191], v[198:199]
	v_cmp_lt_u32_e32 vcc, 9, v173
	s_and_b64 exec, exec, vcc
	v_lshlrev_b32_e32 v192, 16, v80
	v_and_b32_e32 v193, 0xffff0000, v80
	v_lshlrev_b32_e32 v194, 16, v81
	v_and_b32_e32 v195, 0xffff0000, v81
	v_lshlrev_b32_e32 v196, 16, v82
	v_and_b32_e32 v197, 0xffff0000, v82
	v_lshlrev_b32_e32 v198, 16, v83
	v_and_b32_e32 v199, 0xffff0000, v83
	v_pk_add_f32 v[184:185], v[184:185], v[192:193]
	v_pk_add_f32 v[186:187], v[186:187], v[194:195]
	v_pk_add_f32 v[188:189], v[188:189], v[196:197]
	v_pk_add_f32 v[190:191], v[190:191], v[198:199]
	v_cmp_lt_u32_e32 vcc, 10, v173
	s_and_b64 exec, exec, vcc
	v_lshlrev_b32_e32 v192, 16, v76
	v_and_b32_e32 v193, 0xffff0000, v76
	v_lshlrev_b32_e32 v194, 16, v77
	v_and_b32_e32 v195, 0xffff0000, v77
	v_lshlrev_b32_e32 v196, 16, v78
	v_and_b32_e32 v197, 0xffff0000, v78
	v_lshlrev_b32_e32 v198, 16, v79
	v_and_b32_e32 v199, 0xffff0000, v79
	v_pk_add_f32 v[184:185], v[184:185], v[192:193]
	v_pk_add_f32 v[186:187], v[186:187], v[194:195]
	v_pk_add_f32 v[188:189], v[188:189], v[196:197]
	v_pk_add_f32 v[190:191], v[190:191], v[198:199]
	v_cmp_lt_u32_e32 vcc, 11, v173
	s_and_b64 exec, exec, vcc
	v_lshlrev_b32_e32 v192, 16, v72
	v_and_b32_e32 v193, 0xffff0000, v72
	v_lshlrev_b32_e32 v194, 16, v73
	v_and_b32_e32 v195, 0xffff0000, v73
	v_lshlrev_b32_e32 v196, 16, v74
	v_and_b32_e32 v197, 0xffff0000, v74
	v_lshlrev_b32_e32 v198, 16, v75
	v_and_b32_e32 v199, 0xffff0000, v75
	v_pk_add_f32 v[184:185], v[184:185], v[192:193]
	v_pk_add_f32 v[186:187], v[186:187], v[194:195]
	v_pk_add_f32 v[188:189], v[188:189], v[196:197]
	v_pk_add_f32 v[190:191], v[190:191], v[198:199]
	v_cmp_lt_u32_e32 vcc, 12, v173
	s_and_b64 exec, exec, vcc
	v_lshlrev_b32_e32 v192, 16, v68
	v_and_b32_e32 v193, 0xffff0000, v68
	v_lshlrev_b32_e32 v194, 16, v69
	v_and_b32_e32 v195, 0xffff0000, v69
	v_lshlrev_b32_e32 v196, 16, v70
	v_and_b32_e32 v197, 0xffff0000, v70
	v_lshlrev_b32_e32 v198, 16, v71
	v_and_b32_e32 v199, 0xffff0000, v71
	v_pk_add_f32 v[184:185], v[184:185], v[192:193]
	v_pk_add_f32 v[186:187], v[186:187], v[194:195]
	v_pk_add_f32 v[188:189], v[188:189], v[196:197]
	v_pk_add_f32 v[190:191], v[190:191], v[198:199]
	v_cmp_lt_u32_e32 vcc, 13, v173
	s_and_b64 exec, exec, vcc
	v_lshlrev_b32_e32 v192, 16, v64
	v_and_b32_e32 v193, 0xffff0000, v64
	v_lshlrev_b32_e32 v194, 16, v65
	v_and_b32_e32 v195, 0xffff0000, v65
	v_lshlrev_b32_e32 v196, 16, v66
	v_and_b32_e32 v197, 0xffff0000, v66
	v_lshlrev_b32_e32 v198, 16, v67
	v_and_b32_e32 v199, 0xffff0000, v67
	v_pk_add_f32 v[184:185], v[184:185], v[192:193]
	v_pk_add_f32 v[186:187], v[186:187], v[194:195]
	v_pk_add_f32 v[188:189], v[188:189], v[196:197]
	v_pk_add_f32 v[190:191], v[190:191], v[198:199]
	v_cmp_lt_u32_e32 vcc, 14, v173
	s_and_b64 exec, exec, vcc
	v_lshlrev_b32_e32 v192, 16, v60
	v_and_b32_e32 v193, 0xffff0000, v60
	v_lshlrev_b32_e32 v194, 16, v61
	v_and_b32_e32 v195, 0xffff0000, v61
	v_lshlrev_b32_e32 v196, 16, v62
	v_and_b32_e32 v197, 0xffff0000, v62
	v_lshlrev_b32_e32 v198, 16, v63
	v_and_b32_e32 v199, 0xffff0000, v63
	v_pk_add_f32 v[184:185], v[184:185], v[192:193]
	v_pk_add_f32 v[186:187], v[186:187], v[194:195]
	v_pk_add_f32 v[188:189], v[188:189], v[196:197]
	v_pk_add_f32 v[190:191], v[190:191], v[198:199]
	v_cmp_lt_u32_e32 vcc, 15, v173
	s_and_b64 exec, exec, vcc
	v_lshlrev_b32_e32 v192, 16, v56
	v_and_b32_e32 v193, 0xffff0000, v56
	v_lshlrev_b32_e32 v194, 16, v57
	v_and_b32_e32 v195, 0xffff0000, v57
	v_lshlrev_b32_e32 v196, 16, v58
	v_and_b32_e32 v197, 0xffff0000, v58
	v_lshlrev_b32_e32 v198, 16, v59
	v_and_b32_e32 v199, 0xffff0000, v59
	v_pk_add_f32 v[184:185], v[184:185], v[192:193]
	v_pk_add_f32 v[186:187], v[186:187], v[194:195]
	v_pk_add_f32 v[188:189], v[188:189], v[196:197]
	v_pk_add_f32 v[190:191], v[190:191], v[198:199]
	s_mov_b64 exec, s[26:27]
	v_pk_fma_f32 v[184:185], v[184:185], v[174:175], v[176:177] op_sel_hi:[1,0,1] neg_lo:[0,0,1] neg_hi:[0,0,1]
	v_pk_fma_f32 v[186:187], v[186:187], v[174:175], v[178:179] op_sel_hi:[1,0,1] neg_lo:[0,0,1] neg_hi:[0,0,1]
	v_pk_fma_f32 v[188:189], v[188:189], v[174:175], v[180:181] op_sel_hi:[1,0,1] neg_lo:[0,0,1] neg_hi:[0,0,1]
	v_pk_fma_f32 v[190:191], v[190:191], v[174:175], v[182:183] op_sel_hi:[1,0,1] neg_lo:[0,0,1] neg_hi:[0,0,1]
	v_cvt_pk_bf16_f32 v200, v184, v185
	v_cvt_pk_bf16_f32 v201, v186, v187
	v_cvt_pk_bf16_f32 v202, v188, v189
	v_cvt_pk_bf16_f32 v203, v190, v191
	s_add_i32 s21, s20, 3
	s_lshl_b32 s21, s21, 10
	s_add_u32 s24, s88, s21
	s_addc_u32 s25, s89, 0
	global_store_dwordx4 v175, v[200:203], s[24:25]
	s_add_i32 s21, s22, 5
	v_min_u32_e32 v173, s21, v204
	v_cvt_f32_u32_e32 v0, v173
	v_div_scale_f32 v1, s[0:1], v0, v0, 1.0
	v_rcp_f32_e32 v2, v1
	v_div_scale_f32 v3, vcc, 1.0, v0, 1.0
	v_fma_f32 v4, -v1, v2, 1.0
	v_fmac_f32_e32 v2, v4, v2
	v_mul_f32_e32 v4, v3, v2
	v_fma_f32 v5, -v1, v4, v3
	v_fmac_f32_e32 v4, v5, v2
	v_fma_f32 v1, -v1, v4, v3
	v_div_fmas_f32 v1, v1, v2, v4
	v_div_fixup_f32 v174, v1, v0, 1.0
	s_waitcnt vmcnt(7)
	v_lshlrev_b32_e32 v176, 16, v120
	v_and_b32_e32 v177, 0xffff0000, v120
	v_lshlrev_b32_e32 v178, 16, v121
	v_and_b32_e32 v179, 0xffff0000, v121
	v_lshlrev_b32_e32 v180, 16, v122
	v_and_b32_e32 v181, 0xffff0000, v122
	v_lshlrev_b32_e32 v182, 16, v123
	v_and_b32_e32 v183, 0xffff0000, v123
	v_mov_b32_e32 v184, v176
	v_mov_b32_e32 v185, v177
	v_mov_b32_e32 v186, v178
	v_mov_b32_e32 v187, v179
	v_mov_b32_e32 v188, v180
	v_mov_b32_e32 v189, v181
	v_mov_b32_e32 v190, v182
	v_mov_b32_e32 v191, v183
	v_cmp_lt_u32_e32 vcc, 1, v173
	s_and_b64 exec, exec, vcc
	v_lshlrev_b32_e32 v192, 16, v116
	v_and_b32_e32 v193, 0xffff0000, v116
	v_lshlrev_b32_e32 v194, 16, v117
	v_and_b32_e32 v195, 0xffff0000, v117
	v_lshlrev_b32_e32 v196, 16, v118
	v_and_b32_e32 v197, 0xffff0000, v118
	v_lshlrev_b32_e32 v198, 16, v119
	v_and_b32_e32 v199, 0xffff0000, v119
	v_pk_add_f32 v[184:185], v[184:185], v[192:193]
	v_pk_add_f32 v[186:187], v[186:187], v[194:195]
	v_pk_add_f32 v[188:189], v[188:189], v[196:197]
	v_pk_add_f32 v[190:191], v[190:191], v[198:199]
	v_cmp_lt_u32_e32 vcc, 2, v173
	s_and_b64 exec, exec, vcc
	v_lshlrev_b32_e32 v192, 16, v112
	v_and_b32_e32 v193, 0xffff0000, v112
	v_lshlrev_b32_e32 v194, 16, v113
	v_and_b32_e32 v195, 0xffff0000, v113
	v_lshlrev_b32_e32 v196, 16, v114
	v_and_b32_e32 v197, 0xffff0000, v114
	v_lshlrev_b32_e32 v198, 16, v115
	v_and_b32_e32 v199, 0xffff0000, v115
	v_pk_add_f32 v[184:185], v[184:185], v[192:193]
	v_pk_add_f32 v[186:187], v[186:187], v[194:195]
	v_pk_add_f32 v[188:189], v[188:189], v[196:197]
	v_pk_add_f32 v[190:191], v[190:191], v[198:199]
	v_cmp_lt_u32_e32 vcc, 3, v173
	s_and_b64 exec, exec, vcc
	v_lshlrev_b32_e32 v192, 16, v108
	v_and_b32_e32 v193, 0xffff0000, v108
	v_lshlrev_b32_e32 v194, 16, v109
	v_and_b32_e32 v195, 0xffff0000, v109
	v_lshlrev_b32_e32 v196, 16, v110
	v_and_b32_e32 v197, 0xffff0000, v110
	v_lshlrev_b32_e32 v198, 16, v111
	v_and_b32_e32 v199, 0xffff0000, v111
	v_pk_add_f32 v[184:185], v[184:185], v[192:193]
	v_pk_add_f32 v[186:187], v[186:187], v[194:195]
	v_pk_add_f32 v[188:189], v[188:189], v[196:197]
	v_pk_add_f32 v[190:191], v[190:191], v[198:199]
	v_cmp_lt_u32_e32 vcc, 4, v173
	s_and_b64 exec, exec, vcc
	v_lshlrev_b32_e32 v192, 16, v104
	v_and_b32_e32 v193, 0xffff0000, v104
	v_lshlrev_b32_e32 v194, 16, v105
	v_and_b32_e32 v195, 0xffff0000, v105
	v_lshlrev_b32_e32 v196, 16, v106
	v_and_b32_e32 v197, 0xffff0000, v106
	v_lshlrev_b32_e32 v198, 16, v107
	v_and_b32_e32 v199, 0xffff0000, v107
	v_pk_add_f32 v[184:185], v[184:185], v[192:193]
	v_pk_add_f32 v[186:187], v[186:187], v[194:195]
	v_pk_add_f32 v[188:189], v[188:189], v[196:197]
	v_pk_add_f32 v[190:191], v[190:191], v[198:199]
	v_cmp_lt_u32_e32 vcc, 5, v173
	s_and_b64 exec, exec, vcc
	v_lshlrev_b32_e32 v192, 16, v100
	v_and_b32_e32 v193, 0xffff0000, v100
	v_lshlrev_b32_e32 v194, 16, v101
	v_and_b32_e32 v195, 0xffff0000, v101
	v_lshlrev_b32_e32 v196, 16, v102
	v_and_b32_e32 v197, 0xffff0000, v102
	v_lshlrev_b32_e32 v198, 16, v103
	v_and_b32_e32 v199, 0xffff0000, v103
	v_pk_add_f32 v[184:185], v[184:185], v[192:193]
	v_pk_add_f32 v[186:187], v[186:187], v[194:195]
	v_pk_add_f32 v[188:189], v[188:189], v[196:197]
	v_pk_add_f32 v[190:191], v[190:191], v[198:199]
	v_cmp_lt_u32_e32 vcc, 6, v173
	s_and_b64 exec, exec, vcc
	v_lshlrev_b32_e32 v192, 16, v96
	v_and_b32_e32 v193, 0xffff0000, v96
	v_lshlrev_b32_e32 v194, 16, v97
	v_and_b32_e32 v195, 0xffff0000, v97
	v_lshlrev_b32_e32 v196, 16, v98
	v_and_b32_e32 v197, 0xffff0000, v98
	v_lshlrev_b32_e32 v198, 16, v99
	v_and_b32_e32 v199, 0xffff0000, v99
	v_pk_add_f32 v[184:185], v[184:185], v[192:193]
	v_pk_add_f32 v[186:187], v[186:187], v[194:195]
	v_pk_add_f32 v[188:189], v[188:189], v[196:197]
	v_pk_add_f32 v[190:191], v[190:191], v[198:199]
	v_cmp_lt_u32_e32 vcc, 7, v173
	s_and_b64 exec, exec, vcc
	v_lshlrev_b32_e32 v192, 16, v92
	v_and_b32_e32 v193, 0xffff0000, v92
	v_lshlrev_b32_e32 v194, 16, v93
	v_and_b32_e32 v195, 0xffff0000, v93
	v_lshlrev_b32_e32 v196, 16, v94
	v_and_b32_e32 v197, 0xffff0000, v94
	v_lshlrev_b32_e32 v198, 16, v95
	v_and_b32_e32 v199, 0xffff0000, v95
	v_pk_add_f32 v[184:185], v[184:185], v[192:193]
	v_pk_add_f32 v[186:187], v[186:187], v[194:195]
	v_pk_add_f32 v[188:189], v[188:189], v[196:197]
	v_pk_add_f32 v[190:191], v[190:191], v[198:199]
	v_cmp_lt_u32_e32 vcc, 8, v173
	s_and_b64 exec, exec, vcc
	v_lshlrev_b32_e32 v192, 16, v88
	v_and_b32_e32 v193, 0xffff0000, v88
	v_lshlrev_b32_e32 v194, 16, v89
	v_and_b32_e32 v195, 0xffff0000, v89
	v_lshlrev_b32_e32 v196, 16, v90
	v_and_b32_e32 v197, 0xffff0000, v90
	v_lshlrev_b32_e32 v198, 16, v91
	v_and_b32_e32 v199, 0xffff0000, v91
	v_pk_add_f32 v[184:185], v[184:185], v[192:193]
	v_pk_add_f32 v[186:187], v[186:187], v[194:195]
	v_pk_add_f32 v[188:189], v[188:189], v[196:197]
	v_pk_add_f32 v[190:191], v[190:191], v[198:199]
	v_cmp_lt_u32_e32 vcc, 9, v173
	s_and_b64 exec, exec, vcc
	v_lshlrev_b32_e32 v192, 16, v84
	v_and_b32_e32 v193, 0xffff0000, v84
	v_lshlrev_b32_e32 v194, 16, v85
	v_and_b32_e32 v195, 0xffff0000, v85
	v_lshlrev_b32_e32 v196, 16, v86
	v_and_b32_e32 v197, 0xffff0000, v86
	v_lshlrev_b32_e32 v198, 16, v87
	v_and_b32_e32 v199, 0xffff0000, v87
	v_pk_add_f32 v[184:185], v[184:185], v[192:193]
	v_pk_add_f32 v[186:187], v[186:187], v[194:195]
	v_pk_add_f32 v[188:189], v[188:189], v[196:197]
	v_pk_add_f32 v[190:191], v[190:191], v[198:199]
	v_cmp_lt_u32_e32 vcc, 10, v173
	s_and_b64 exec, exec, vcc
	v_lshlrev_b32_e32 v192, 16, v80
	v_and_b32_e32 v193, 0xffff0000, v80
	v_lshlrev_b32_e32 v194, 16, v81
	v_and_b32_e32 v195, 0xffff0000, v81
	v_lshlrev_b32_e32 v196, 16, v82
	v_and_b32_e32 v197, 0xffff0000, v82
	v_lshlrev_b32_e32 v198, 16, v83
	v_and_b32_e32 v199, 0xffff0000, v83
	v_pk_add_f32 v[184:185], v[184:185], v[192:193]
	v_pk_add_f32 v[186:187], v[186:187], v[194:195]
	v_pk_add_f32 v[188:189], v[188:189], v[196:197]
	v_pk_add_f32 v[190:191], v[190:191], v[198:199]
	v_cmp_lt_u32_e32 vcc, 11, v173
	s_and_b64 exec, exec, vcc
	v_lshlrev_b32_e32 v192, 16, v76
	v_and_b32_e32 v193, 0xffff0000, v76
	v_lshlrev_b32_e32 v194, 16, v77
	v_and_b32_e32 v195, 0xffff0000, v77
	v_lshlrev_b32_e32 v196, 16, v78
	v_and_b32_e32 v197, 0xffff0000, v78
	v_lshlrev_b32_e32 v198, 16, v79
	v_and_b32_e32 v199, 0xffff0000, v79
	v_pk_add_f32 v[184:185], v[184:185], v[192:193]
	v_pk_add_f32 v[186:187], v[186:187], v[194:195]
	v_pk_add_f32 v[188:189], v[188:189], v[196:197]
	v_pk_add_f32 v[190:191], v[190:191], v[198:199]
	v_cmp_lt_u32_e32 vcc, 12, v173
	s_and_b64 exec, exec, vcc
	v_lshlrev_b32_e32 v192, 16, v72
	v_and_b32_e32 v193, 0xffff0000, v72
	v_lshlrev_b32_e32 v194, 16, v73
	v_and_b32_e32 v195, 0xffff0000, v73
	v_lshlrev_b32_e32 v196, 16, v74
	v_and_b32_e32 v197, 0xffff0000, v74
	v_lshlrev_b32_e32 v198, 16, v75
	v_and_b32_e32 v199, 0xffff0000, v75
	v_pk_add_f32 v[184:185], v[184:185], v[192:193]
	v_pk_add_f32 v[186:187], v[186:187], v[194:195]
	v_pk_add_f32 v[188:189], v[188:189], v[196:197]
	v_pk_add_f32 v[190:191], v[190:191], v[198:199]
	v_cmp_lt_u32_e32 vcc, 13, v173
	s_and_b64 exec, exec, vcc
	v_lshlrev_b32_e32 v192, 16, v68
	v_and_b32_e32 v193, 0xffff0000, v68
	v_lshlrev_b32_e32 v194, 16, v69
	v_and_b32_e32 v195, 0xffff0000, v69
	v_lshlrev_b32_e32 v196, 16, v70
	v_and_b32_e32 v197, 0xffff0000, v70
	v_lshlrev_b32_e32 v198, 16, v71
	v_and_b32_e32 v199, 0xffff0000, v71
	v_pk_add_f32 v[184:185], v[184:185], v[192:193]
	v_pk_add_f32 v[186:187], v[186:187], v[194:195]
	v_pk_add_f32 v[188:189], v[188:189], v[196:197]
	v_pk_add_f32 v[190:191], v[190:191], v[198:199]
	v_cmp_lt_u32_e32 vcc, 14, v173
	s_and_b64 exec, exec, vcc
	v_lshlrev_b32_e32 v192, 16, v64
	v_and_b32_e32 v193, 0xffff0000, v64
	v_lshlrev_b32_e32 v194, 16, v65
	v_and_b32_e32 v195, 0xffff0000, v65
	v_lshlrev_b32_e32 v196, 16, v66
	v_and_b32_e32 v197, 0xffff0000, v66
	v_lshlrev_b32_e32 v198, 16, v67
	v_and_b32_e32 v199, 0xffff0000, v67
	v_pk_add_f32 v[184:185], v[184:185], v[192:193]
	v_pk_add_f32 v[186:187], v[186:187], v[194:195]
	v_pk_add_f32 v[188:189], v[188:189], v[196:197]
	v_pk_add_f32 v[190:191], v[190:191], v[198:199]
	v_cmp_lt_u32_e32 vcc, 15, v173
	s_and_b64 exec, exec, vcc
	v_lshlrev_b32_e32 v192, 16, v60
	v_and_b32_e32 v193, 0xffff0000, v60
	v_lshlrev_b32_e32 v194, 16, v61
	v_and_b32_e32 v195, 0xffff0000, v61
	v_lshlrev_b32_e32 v196, 16, v62
	v_and_b32_e32 v197, 0xffff0000, v62
	v_lshlrev_b32_e32 v198, 16, v63
	v_and_b32_e32 v199, 0xffff0000, v63
	v_pk_add_f32 v[184:185], v[184:185], v[192:193]
	v_pk_add_f32 v[186:187], v[186:187], v[194:195]
	v_pk_add_f32 v[188:189], v[188:189], v[196:197]
	v_pk_add_f32 v[190:191], v[190:191], v[198:199]
	s_mov_b64 exec, s[26:27]
	v_pk_fma_f32 v[184:185], v[184:185], v[174:175], v[176:177] op_sel_hi:[1,0,1] neg_lo:[0,0,1] neg_hi:[0,0,1]
	v_pk_fma_f32 v[186:187], v[186:187], v[174:175], v[178:179] op_sel_hi:[1,0,1] neg_lo:[0,0,1] neg_hi:[0,0,1]
	v_pk_fma_f32 v[188:189], v[188:189], v[174:175], v[180:181] op_sel_hi:[1,0,1] neg_lo:[0,0,1] neg_hi:[0,0,1]
	v_pk_fma_f32 v[190:191], v[190:191], v[174:175], v[182:183] op_sel_hi:[1,0,1] neg_lo:[0,0,1] neg_hi:[0,0,1]
	v_cvt_pk_bf16_f32 v200, v184, v185
	v_cvt_pk_bf16_f32 v201, v186, v187
	v_cvt_pk_bf16_f32 v202, v188, v189
	v_cvt_pk_bf16_f32 v203, v190, v191
	s_add_i32 s21, s20, 4
	s_lshl_b32 s21, s21, 10
	s_add_u32 s24, s88, s21
	s_addc_u32 s25, s89, 0
	global_store_dwordx4 v175, v[200:203], s[24:25]
	s_add_i32 s21, s22, 6
	v_min_u32_e32 v173, s21, v204
	v_cvt_f32_u32_e32 v0, v173
	v_div_scale_f32 v1, s[0:1], v0, v0, 1.0
	v_rcp_f32_e32 v2, v1
	v_div_scale_f32 v3, vcc, 1.0, v0, 1.0
	v_fma_f32 v4, -v1, v2, 1.0
	v_fmac_f32_e32 v2, v4, v2
	v_mul_f32_e32 v4, v3, v2
	v_fma_f32 v5, -v1, v4, v3
	v_fmac_f32_e32 v4, v5, v2
	v_fma_f32 v1, -v1, v4, v3
	v_div_fmas_f32 v1, v1, v2, v4
	v_div_fixup_f32 v174, v1, v0, 1.0
	s_waitcnt vmcnt(7)
	v_lshlrev_b32_e32 v176, 16, v124
	v_and_b32_e32 v177, 0xffff0000, v124
	v_lshlrev_b32_e32 v178, 16, v125
	v_and_b32_e32 v179, 0xffff0000, v125
	v_lshlrev_b32_e32 v180, 16, v126
	v_and_b32_e32 v181, 0xffff0000, v126
	v_lshlrev_b32_e32 v182, 16, v127
	v_and_b32_e32 v183, 0xffff0000, v127
	v_mov_b32_e32 v184, v176
	v_mov_b32_e32 v185, v177
	v_mov_b32_e32 v186, v178
	v_mov_b32_e32 v187, v179
	v_mov_b32_e32 v188, v180
	v_mov_b32_e32 v189, v181
	v_mov_b32_e32 v190, v182
	v_mov_b32_e32 v191, v183
	v_cmp_lt_u32_e32 vcc, 1, v173
	s_and_b64 exec, exec, vcc
	v_lshlrev_b32_e32 v192, 16, v120
	v_and_b32_e32 v193, 0xffff0000, v120
	v_lshlrev_b32_e32 v194, 16, v121
	v_and_b32_e32 v195, 0xffff0000, v121
	v_lshlrev_b32_e32 v196, 16, v122
	v_and_b32_e32 v197, 0xffff0000, v122
	v_lshlrev_b32_e32 v198, 16, v123
	v_and_b32_e32 v199, 0xffff0000, v123
	v_pk_add_f32 v[184:185], v[184:185], v[192:193]
	v_pk_add_f32 v[186:187], v[186:187], v[194:195]
	v_pk_add_f32 v[188:189], v[188:189], v[196:197]
	v_pk_add_f32 v[190:191], v[190:191], v[198:199]
	v_cmp_lt_u32_e32 vcc, 2, v173
	s_and_b64 exec, exec, vcc
	v_lshlrev_b32_e32 v192, 16, v116
	v_and_b32_e32 v193, 0xffff0000, v116
	v_lshlrev_b32_e32 v194, 16, v117
	v_and_b32_e32 v195, 0xffff0000, v117
	v_lshlrev_b32_e32 v196, 16, v118
	v_and_b32_e32 v197, 0xffff0000, v118
	v_lshlrev_b32_e32 v198, 16, v119
	v_and_b32_e32 v199, 0xffff0000, v119
	v_pk_add_f32 v[184:185], v[184:185], v[192:193]
	v_pk_add_f32 v[186:187], v[186:187], v[194:195]
	v_pk_add_f32 v[188:189], v[188:189], v[196:197]
	v_pk_add_f32 v[190:191], v[190:191], v[198:199]
	v_cmp_lt_u32_e32 vcc, 3, v173
	s_and_b64 exec, exec, vcc
	v_lshlrev_b32_e32 v192, 16, v112
	v_and_b32_e32 v193, 0xffff0000, v112
	v_lshlrev_b32_e32 v194, 16, v113
	v_and_b32_e32 v195, 0xffff0000, v113
	v_lshlrev_b32_e32 v196, 16, v114
	v_and_b32_e32 v197, 0xffff0000, v114
	v_lshlrev_b32_e32 v198, 16, v115
	v_and_b32_e32 v199, 0xffff0000, v115
	v_pk_add_f32 v[184:185], v[184:185], v[192:193]
	v_pk_add_f32 v[186:187], v[186:187], v[194:195]
	v_pk_add_f32 v[188:189], v[188:189], v[196:197]
	v_pk_add_f32 v[190:191], v[190:191], v[198:199]
	v_cmp_lt_u32_e32 vcc, 4, v173
	s_and_b64 exec, exec, vcc
	v_lshlrev_b32_e32 v192, 16, v108
	v_and_b32_e32 v193, 0xffff0000, v108
	v_lshlrev_b32_e32 v194, 16, v109
	v_and_b32_e32 v195, 0xffff0000, v109
	v_lshlrev_b32_e32 v196, 16, v110
	v_and_b32_e32 v197, 0xffff0000, v110
	v_lshlrev_b32_e32 v198, 16, v111
	v_and_b32_e32 v199, 0xffff0000, v111
	v_pk_add_f32 v[184:185], v[184:185], v[192:193]
	v_pk_add_f32 v[186:187], v[186:187], v[194:195]
	v_pk_add_f32 v[188:189], v[188:189], v[196:197]
	v_pk_add_f32 v[190:191], v[190:191], v[198:199]
	v_cmp_lt_u32_e32 vcc, 5, v173
	s_and_b64 exec, exec, vcc
	v_lshlrev_b32_e32 v192, 16, v104
	v_and_b32_e32 v193, 0xffff0000, v104
	v_lshlrev_b32_e32 v194, 16, v105
	v_and_b32_e32 v195, 0xffff0000, v105
	v_lshlrev_b32_e32 v196, 16, v106
	v_and_b32_e32 v197, 0xffff0000, v106
	v_lshlrev_b32_e32 v198, 16, v107
	v_and_b32_e32 v199, 0xffff0000, v107
	v_pk_add_f32 v[184:185], v[184:185], v[192:193]
	v_pk_add_f32 v[186:187], v[186:187], v[194:195]
	v_pk_add_f32 v[188:189], v[188:189], v[196:197]
	v_pk_add_f32 v[190:191], v[190:191], v[198:199]
	v_cmp_lt_u32_e32 vcc, 6, v173
	s_and_b64 exec, exec, vcc
	v_lshlrev_b32_e32 v192, 16, v100
	v_and_b32_e32 v193, 0xffff0000, v100
	v_lshlrev_b32_e32 v194, 16, v101
	v_and_b32_e32 v195, 0xffff0000, v101
	v_lshlrev_b32_e32 v196, 16, v102
	v_and_b32_e32 v197, 0xffff0000, v102
	v_lshlrev_b32_e32 v198, 16, v103
	v_and_b32_e32 v199, 0xffff0000, v103
	v_pk_add_f32 v[184:185], v[184:185], v[192:193]
	v_pk_add_f32 v[186:187], v[186:187], v[194:195]
	v_pk_add_f32 v[188:189], v[188:189], v[196:197]
	v_pk_add_f32 v[190:191], v[190:191], v[198:199]
	v_cmp_lt_u32_e32 vcc, 7, v173
	s_and_b64 exec, exec, vcc
	v_lshlrev_b32_e32 v192, 16, v96
	v_and_b32_e32 v193, 0xffff0000, v96
	v_lshlrev_b32_e32 v194, 16, v97
	v_and_b32_e32 v195, 0xffff0000, v97
	v_lshlrev_b32_e32 v196, 16, v98
	v_and_b32_e32 v197, 0xffff0000, v98
	v_lshlrev_b32_e32 v198, 16, v99
	v_and_b32_e32 v199, 0xffff0000, v99
	v_pk_add_f32 v[184:185], v[184:185], v[192:193]
	v_pk_add_f32 v[186:187], v[186:187], v[194:195]
	v_pk_add_f32 v[188:189], v[188:189], v[196:197]
	v_pk_add_f32 v[190:191], v[190:191], v[198:199]
	v_cmp_lt_u32_e32 vcc, 8, v173
	s_and_b64 exec, exec, vcc
	v_lshlrev_b32_e32 v192, 16, v92
	v_and_b32_e32 v193, 0xffff0000, v92
	v_lshlrev_b32_e32 v194, 16, v93
	v_and_b32_e32 v195, 0xffff0000, v93
	v_lshlrev_b32_e32 v196, 16, v94
	v_and_b32_e32 v197, 0xffff0000, v94
	v_lshlrev_b32_e32 v198, 16, v95
	v_and_b32_e32 v199, 0xffff0000, v95
	v_pk_add_f32 v[184:185], v[184:185], v[192:193]
	v_pk_add_f32 v[186:187], v[186:187], v[194:195]
	v_pk_add_f32 v[188:189], v[188:189], v[196:197]
	v_pk_add_f32 v[190:191], v[190:191], v[198:199]
	v_cmp_lt_u32_e32 vcc, 9, v173
	s_and_b64 exec, exec, vcc
	v_lshlrev_b32_e32 v192, 16, v88
	v_and_b32_e32 v193, 0xffff0000, v88
	v_lshlrev_b32_e32 v194, 16, v89
	v_and_b32_e32 v195, 0xffff0000, v89
	v_lshlrev_b32_e32 v196, 16, v90
	v_and_b32_e32 v197, 0xffff0000, v90
	v_lshlrev_b32_e32 v198, 16, v91
	v_and_b32_e32 v199, 0xffff0000, v91
	v_pk_add_f32 v[184:185], v[184:185], v[192:193]
	v_pk_add_f32 v[186:187], v[186:187], v[194:195]
	v_pk_add_f32 v[188:189], v[188:189], v[196:197]
	v_pk_add_f32 v[190:191], v[190:191], v[198:199]
	v_cmp_lt_u32_e32 vcc, 10, v173
	s_and_b64 exec, exec, vcc
	v_lshlrev_b32_e32 v192, 16, v84
	v_and_b32_e32 v193, 0xffff0000, v84
	v_lshlrev_b32_e32 v194, 16, v85
	v_and_b32_e32 v195, 0xffff0000, v85
	v_lshlrev_b32_e32 v196, 16, v86
	v_and_b32_e32 v197, 0xffff0000, v86
	v_lshlrev_b32_e32 v198, 16, v87
	v_and_b32_e32 v199, 0xffff0000, v87
	v_pk_add_f32 v[184:185], v[184:185], v[192:193]
	v_pk_add_f32 v[186:187], v[186:187], v[194:195]
	v_pk_add_f32 v[188:189], v[188:189], v[196:197]
	v_pk_add_f32 v[190:191], v[190:191], v[198:199]
	v_cmp_lt_u32_e32 vcc, 11, v173
	s_and_b64 exec, exec, vcc
	v_lshlrev_b32_e32 v192, 16, v80
	v_and_b32_e32 v193, 0xffff0000, v80
	v_lshlrev_b32_e32 v194, 16, v81
	v_and_b32_e32 v195, 0xffff0000, v81
	v_lshlrev_b32_e32 v196, 16, v82
	v_and_b32_e32 v197, 0xffff0000, v82
	v_lshlrev_b32_e32 v198, 16, v83
	v_and_b32_e32 v199, 0xffff0000, v83
	v_pk_add_f32 v[184:185], v[184:185], v[192:193]
	v_pk_add_f32 v[186:187], v[186:187], v[194:195]
	v_pk_add_f32 v[188:189], v[188:189], v[196:197]
	v_pk_add_f32 v[190:191], v[190:191], v[198:199]
	v_cmp_lt_u32_e32 vcc, 12, v173
	s_and_b64 exec, exec, vcc
	v_lshlrev_b32_e32 v192, 16, v76
	v_and_b32_e32 v193, 0xffff0000, v76
	v_lshlrev_b32_e32 v194, 16, v77
	v_and_b32_e32 v195, 0xffff0000, v77
	v_lshlrev_b32_e32 v196, 16, v78
	v_and_b32_e32 v197, 0xffff0000, v78
	v_lshlrev_b32_e32 v198, 16, v79
	v_and_b32_e32 v199, 0xffff0000, v79
	v_pk_add_f32 v[184:185], v[184:185], v[192:193]
	v_pk_add_f32 v[186:187], v[186:187], v[194:195]
	v_pk_add_f32 v[188:189], v[188:189], v[196:197]
	v_pk_add_f32 v[190:191], v[190:191], v[198:199]
	v_cmp_lt_u32_e32 vcc, 13, v173
	s_and_b64 exec, exec, vcc
	v_lshlrev_b32_e32 v192, 16, v72
	v_and_b32_e32 v193, 0xffff0000, v72
	v_lshlrev_b32_e32 v194, 16, v73
	v_and_b32_e32 v195, 0xffff0000, v73
	v_lshlrev_b32_e32 v196, 16, v74
	v_and_b32_e32 v197, 0xffff0000, v74
	v_lshlrev_b32_e32 v198, 16, v75
	v_and_b32_e32 v199, 0xffff0000, v75
	v_pk_add_f32 v[184:185], v[184:185], v[192:193]
	v_pk_add_f32 v[186:187], v[186:187], v[194:195]
	v_pk_add_f32 v[188:189], v[188:189], v[196:197]
	v_pk_add_f32 v[190:191], v[190:191], v[198:199]
	v_cmp_lt_u32_e32 vcc, 14, v173
	s_and_b64 exec, exec, vcc
	v_lshlrev_b32_e32 v192, 16, v68
	v_and_b32_e32 v193, 0xffff0000, v68
	v_lshlrev_b32_e32 v194, 16, v69
	v_and_b32_e32 v195, 0xffff0000, v69
	v_lshlrev_b32_e32 v196, 16, v70
	v_and_b32_e32 v197, 0xffff0000, v70
	v_lshlrev_b32_e32 v198, 16, v71
	v_and_b32_e32 v199, 0xffff0000, v71
	v_pk_add_f32 v[184:185], v[184:185], v[192:193]
	v_pk_add_f32 v[186:187], v[186:187], v[194:195]
	v_pk_add_f32 v[188:189], v[188:189], v[196:197]
	v_pk_add_f32 v[190:191], v[190:191], v[198:199]
	v_cmp_lt_u32_e32 vcc, 15, v173
	s_and_b64 exec, exec, vcc
	v_lshlrev_b32_e32 v192, 16, v64
	v_and_b32_e32 v193, 0xffff0000, v64
	v_lshlrev_b32_e32 v194, 16, v65
	v_and_b32_e32 v195, 0xffff0000, v65
	v_lshlrev_b32_e32 v196, 16, v66
	v_and_b32_e32 v197, 0xffff0000, v66
	v_lshlrev_b32_e32 v198, 16, v67
	v_and_b32_e32 v199, 0xffff0000, v67
	v_pk_add_f32 v[184:185], v[184:185], v[192:193]
	v_pk_add_f32 v[186:187], v[186:187], v[194:195]
	v_pk_add_f32 v[188:189], v[188:189], v[196:197]
	v_pk_add_f32 v[190:191], v[190:191], v[198:199]
	s_mov_b64 exec, s[26:27]
	v_pk_fma_f32 v[184:185], v[184:185], v[174:175], v[176:177] op_sel_hi:[1,0,1] neg_lo:[0,0,1] neg_hi:[0,0,1]
	v_pk_fma_f32 v[186:187], v[186:187], v[174:175], v[178:179] op_sel_hi:[1,0,1] neg_lo:[0,0,1] neg_hi:[0,0,1]
	v_pk_fma_f32 v[188:189], v[188:189], v[174:175], v[180:181] op_sel_hi:[1,0,1] neg_lo:[0,0,1] neg_hi:[0,0,1]
	v_pk_fma_f32 v[190:191], v[190:191], v[174:175], v[182:183] op_sel_hi:[1,0,1] neg_lo:[0,0,1] neg_hi:[0,0,1]
	v_cvt_pk_bf16_f32 v200, v184, v185
	v_cvt_pk_bf16_f32 v201, v186, v187
	v_cvt_pk_bf16_f32 v202, v188, v189
	v_cvt_pk_bf16_f32 v203, v190, v191
	s_add_i32 s21, s20, 5
	s_lshl_b32 s21, s21, 10
	s_add_u32 s24, s88, s21
	s_addc_u32 s25, s89, 0
	global_store_dwordx4 v175, v[200:203], s[24:25]
	s_add_i32 s21, s22, 7
	v_min_u32_e32 v173, s21, v204
	v_cvt_f32_u32_e32 v0, v173
	v_div_scale_f32 v1, s[0:1], v0, v0, 1.0
	v_rcp_f32_e32 v2, v1
	v_div_scale_f32 v3, vcc, 1.0, v0, 1.0
	v_fma_f32 v4, -v1, v2, 1.0
	v_fmac_f32_e32 v2, v4, v2
	v_mul_f32_e32 v4, v3, v2
	v_fma_f32 v5, -v1, v4, v3
	v_fmac_f32_e32 v4, v5, v2
	v_fma_f32 v1, -v1, v4, v3
	v_div_fmas_f32 v1, v1, v2, v4
	v_div_fixup_f32 v174, v1, v0, 1.0
	s_waitcnt vmcnt(7)
	v_lshlrev_b32_e32 v176, 16, v128
	v_and_b32_e32 v177, 0xffff0000, v128
	v_lshlrev_b32_e32 v178, 16, v129
	v_and_b32_e32 v179, 0xffff0000, v129
	v_lshlrev_b32_e32 v180, 16, v130
	v_and_b32_e32 v181, 0xffff0000, v130
	v_lshlrev_b32_e32 v182, 16, v131
	v_and_b32_e32 v183, 0xffff0000, v131
	v_mov_b32_e32 v184, v176
	v_mov_b32_e32 v185, v177
	v_mov_b32_e32 v186, v178
	v_mov_b32_e32 v187, v179
	v_mov_b32_e32 v188, v180
	v_mov_b32_e32 v189, v181
	v_mov_b32_e32 v190, v182
	v_mov_b32_e32 v191, v183
	v_cmp_lt_u32_e32 vcc, 1, v173
	s_and_b64 exec, exec, vcc
	v_lshlrev_b32_e32 v192, 16, v124
	v_and_b32_e32 v193, 0xffff0000, v124
	v_lshlrev_b32_e32 v194, 16, v125
	v_and_b32_e32 v195, 0xffff0000, v125
	v_lshlrev_b32_e32 v196, 16, v126
	v_and_b32_e32 v197, 0xffff0000, v126
	v_lshlrev_b32_e32 v198, 16, v127
	v_and_b32_e32 v199, 0xffff0000, v127
	v_pk_add_f32 v[184:185], v[184:185], v[192:193]
	v_pk_add_f32 v[186:187], v[186:187], v[194:195]
	v_pk_add_f32 v[188:189], v[188:189], v[196:197]
	v_pk_add_f32 v[190:191], v[190:191], v[198:199]
	v_cmp_lt_u32_e32 vcc, 2, v173
	s_and_b64 exec, exec, vcc
	v_lshlrev_b32_e32 v192, 16, v120
	v_and_b32_e32 v193, 0xffff0000, v120
	v_lshlrev_b32_e32 v194, 16, v121
	v_and_b32_e32 v195, 0xffff0000, v121
	v_lshlrev_b32_e32 v196, 16, v122
	v_and_b32_e32 v197, 0xffff0000, v122
	v_lshlrev_b32_e32 v198, 16, v123
	v_and_b32_e32 v199, 0xffff0000, v123
	v_pk_add_f32 v[184:185], v[184:185], v[192:193]
	v_pk_add_f32 v[186:187], v[186:187], v[194:195]
	v_pk_add_f32 v[188:189], v[188:189], v[196:197]
	v_pk_add_f32 v[190:191], v[190:191], v[198:199]
	v_cmp_lt_u32_e32 vcc, 3, v173
	s_and_b64 exec, exec, vcc
	v_lshlrev_b32_e32 v192, 16, v116
	v_and_b32_e32 v193, 0xffff0000, v116
	v_lshlrev_b32_e32 v194, 16, v117
	v_and_b32_e32 v195, 0xffff0000, v117
	v_lshlrev_b32_e32 v196, 16, v118
	v_and_b32_e32 v197, 0xffff0000, v118
	v_lshlrev_b32_e32 v198, 16, v119
	v_and_b32_e32 v199, 0xffff0000, v119
	v_pk_add_f32 v[184:185], v[184:185], v[192:193]
	v_pk_add_f32 v[186:187], v[186:187], v[194:195]
	v_pk_add_f32 v[188:189], v[188:189], v[196:197]
	v_pk_add_f32 v[190:191], v[190:191], v[198:199]
	v_cmp_lt_u32_e32 vcc, 4, v173
	s_and_b64 exec, exec, vcc
	v_lshlrev_b32_e32 v192, 16, v112
	v_and_b32_e32 v193, 0xffff0000, v112
	v_lshlrev_b32_e32 v194, 16, v113
	v_and_b32_e32 v195, 0xffff0000, v113
	v_lshlrev_b32_e32 v196, 16, v114
	v_and_b32_e32 v197, 0xffff0000, v114
	v_lshlrev_b32_e32 v198, 16, v115
	v_and_b32_e32 v199, 0xffff0000, v115
	v_pk_add_f32 v[184:185], v[184:185], v[192:193]
	v_pk_add_f32 v[186:187], v[186:187], v[194:195]
	v_pk_add_f32 v[188:189], v[188:189], v[196:197]
	v_pk_add_f32 v[190:191], v[190:191], v[198:199]
	v_cmp_lt_u32_e32 vcc, 5, v173
	s_and_b64 exec, exec, vcc
	v_lshlrev_b32_e32 v192, 16, v108
	v_and_b32_e32 v193, 0xffff0000, v108
	v_lshlrev_b32_e32 v194, 16, v109
	v_and_b32_e32 v195, 0xffff0000, v109
	v_lshlrev_b32_e32 v196, 16, v110
	v_and_b32_e32 v197, 0xffff0000, v110
	v_lshlrev_b32_e32 v198, 16, v111
	v_and_b32_e32 v199, 0xffff0000, v111
	v_pk_add_f32 v[184:185], v[184:185], v[192:193]
	v_pk_add_f32 v[186:187], v[186:187], v[194:195]
	v_pk_add_f32 v[188:189], v[188:189], v[196:197]
	v_pk_add_f32 v[190:191], v[190:191], v[198:199]
	v_cmp_lt_u32_e32 vcc, 6, v173
	s_and_b64 exec, exec, vcc
	v_lshlrev_b32_e32 v192, 16, v104
	v_and_b32_e32 v193, 0xffff0000, v104
	v_lshlrev_b32_e32 v194, 16, v105
	v_and_b32_e32 v195, 0xffff0000, v105
	v_lshlrev_b32_e32 v196, 16, v106
	v_and_b32_e32 v197, 0xffff0000, v106
	v_lshlrev_b32_e32 v198, 16, v107
	v_and_b32_e32 v199, 0xffff0000, v107
	v_pk_add_f32 v[184:185], v[184:185], v[192:193]
	v_pk_add_f32 v[186:187], v[186:187], v[194:195]
	v_pk_add_f32 v[188:189], v[188:189], v[196:197]
	v_pk_add_f32 v[190:191], v[190:191], v[198:199]
	v_cmp_lt_u32_e32 vcc, 7, v173
	s_and_b64 exec, exec, vcc
	v_lshlrev_b32_e32 v192, 16, v100
	v_and_b32_e32 v193, 0xffff0000, v100
	v_lshlrev_b32_e32 v194, 16, v101
	v_and_b32_e32 v195, 0xffff0000, v101
	v_lshlrev_b32_e32 v196, 16, v102
	v_and_b32_e32 v197, 0xffff0000, v102
	v_lshlrev_b32_e32 v198, 16, v103
	v_and_b32_e32 v199, 0xffff0000, v103
	v_pk_add_f32 v[184:185], v[184:185], v[192:193]
	v_pk_add_f32 v[186:187], v[186:187], v[194:195]
	v_pk_add_f32 v[188:189], v[188:189], v[196:197]
	v_pk_add_f32 v[190:191], v[190:191], v[198:199]
	v_cmp_lt_u32_e32 vcc, 8, v173
	s_and_b64 exec, exec, vcc
	v_lshlrev_b32_e32 v192, 16, v96
	v_and_b32_e32 v193, 0xffff0000, v96
	v_lshlrev_b32_e32 v194, 16, v97
	v_and_b32_e32 v195, 0xffff0000, v97
	v_lshlrev_b32_e32 v196, 16, v98
	v_and_b32_e32 v197, 0xffff0000, v98
	v_lshlrev_b32_e32 v198, 16, v99
	v_and_b32_e32 v199, 0xffff0000, v99
	v_pk_add_f32 v[184:185], v[184:185], v[192:193]
	v_pk_add_f32 v[186:187], v[186:187], v[194:195]
	v_pk_add_f32 v[188:189], v[188:189], v[196:197]
	v_pk_add_f32 v[190:191], v[190:191], v[198:199]
	v_cmp_lt_u32_e32 vcc, 9, v173
	s_and_b64 exec, exec, vcc
	v_lshlrev_b32_e32 v192, 16, v92
	v_and_b32_e32 v193, 0xffff0000, v92
	v_lshlrev_b32_e32 v194, 16, v93
	v_and_b32_e32 v195, 0xffff0000, v93
	v_lshlrev_b32_e32 v196, 16, v94
	v_and_b32_e32 v197, 0xffff0000, v94
	v_lshlrev_b32_e32 v198, 16, v95
	v_and_b32_e32 v199, 0xffff0000, v95
	v_pk_add_f32 v[184:185], v[184:185], v[192:193]
	v_pk_add_f32 v[186:187], v[186:187], v[194:195]
	v_pk_add_f32 v[188:189], v[188:189], v[196:197]
	v_pk_add_f32 v[190:191], v[190:191], v[198:199]
	v_cmp_lt_u32_e32 vcc, 10, v173
	s_and_b64 exec, exec, vcc
	v_lshlrev_b32_e32 v192, 16, v88
	v_and_b32_e32 v193, 0xffff0000, v88
	v_lshlrev_b32_e32 v194, 16, v89
	v_and_b32_e32 v195, 0xffff0000, v89
	v_lshlrev_b32_e32 v196, 16, v90
	v_and_b32_e32 v197, 0xffff0000, v90
	v_lshlrev_b32_e32 v198, 16, v91
	v_and_b32_e32 v199, 0xffff0000, v91
	v_pk_add_f32 v[184:185], v[184:185], v[192:193]
	v_pk_add_f32 v[186:187], v[186:187], v[194:195]
	v_pk_add_f32 v[188:189], v[188:189], v[196:197]
	v_pk_add_f32 v[190:191], v[190:191], v[198:199]
	v_cmp_lt_u32_e32 vcc, 11, v173
	s_and_b64 exec, exec, vcc
	v_lshlrev_b32_e32 v192, 16, v84
	v_and_b32_e32 v193, 0xffff0000, v84
	v_lshlrev_b32_e32 v194, 16, v85
	v_and_b32_e32 v195, 0xffff0000, v85
	v_lshlrev_b32_e32 v196, 16, v86
	v_and_b32_e32 v197, 0xffff0000, v86
	v_lshlrev_b32_e32 v198, 16, v87
	v_and_b32_e32 v199, 0xffff0000, v87
	v_pk_add_f32 v[184:185], v[184:185], v[192:193]
	v_pk_add_f32 v[186:187], v[186:187], v[194:195]
	v_pk_add_f32 v[188:189], v[188:189], v[196:197]
	v_pk_add_f32 v[190:191], v[190:191], v[198:199]
	v_cmp_lt_u32_e32 vcc, 12, v173
	s_and_b64 exec, exec, vcc
	v_lshlrev_b32_e32 v192, 16, v80
	v_and_b32_e32 v193, 0xffff0000, v80
	v_lshlrev_b32_e32 v194, 16, v81
	v_and_b32_e32 v195, 0xffff0000, v81
	v_lshlrev_b32_e32 v196, 16, v82
	v_and_b32_e32 v197, 0xffff0000, v82
	v_lshlrev_b32_e32 v198, 16, v83
	v_and_b32_e32 v199, 0xffff0000, v83
	v_pk_add_f32 v[184:185], v[184:185], v[192:193]
	v_pk_add_f32 v[186:187], v[186:187], v[194:195]
	v_pk_add_f32 v[188:189], v[188:189], v[196:197]
	v_pk_add_f32 v[190:191], v[190:191], v[198:199]
	v_cmp_lt_u32_e32 vcc, 13, v173
	s_and_b64 exec, exec, vcc
	v_lshlrev_b32_e32 v192, 16, v76
	v_and_b32_e32 v193, 0xffff0000, v76
	v_lshlrev_b32_e32 v194, 16, v77
	v_and_b32_e32 v195, 0xffff0000, v77
	v_lshlrev_b32_e32 v196, 16, v78
	v_and_b32_e32 v197, 0xffff0000, v78
	v_lshlrev_b32_e32 v198, 16, v79
	v_and_b32_e32 v199, 0xffff0000, v79
	v_pk_add_f32 v[184:185], v[184:185], v[192:193]
	v_pk_add_f32 v[186:187], v[186:187], v[194:195]
	v_pk_add_f32 v[188:189], v[188:189], v[196:197]
	v_pk_add_f32 v[190:191], v[190:191], v[198:199]
	v_cmp_lt_u32_e32 vcc, 14, v173
	s_and_b64 exec, exec, vcc
	v_lshlrev_b32_e32 v192, 16, v72
	v_and_b32_e32 v193, 0xffff0000, v72
	v_lshlrev_b32_e32 v194, 16, v73
	v_and_b32_e32 v195, 0xffff0000, v73
	v_lshlrev_b32_e32 v196, 16, v74
	v_and_b32_e32 v197, 0xffff0000, v74
	v_lshlrev_b32_e32 v198, 16, v75
	v_and_b32_e32 v199, 0xffff0000, v75
	v_pk_add_f32 v[184:185], v[184:185], v[192:193]
	v_pk_add_f32 v[186:187], v[186:187], v[194:195]
	v_pk_add_f32 v[188:189], v[188:189], v[196:197]
	v_pk_add_f32 v[190:191], v[190:191], v[198:199]
	v_cmp_lt_u32_e32 vcc, 15, v173
	s_and_b64 exec, exec, vcc
	v_lshlrev_b32_e32 v192, 16, v68
	v_and_b32_e32 v193, 0xffff0000, v68
	v_lshlrev_b32_e32 v194, 16, v69
	v_and_b32_e32 v195, 0xffff0000, v69
	v_lshlrev_b32_e32 v196, 16, v70
	v_and_b32_e32 v197, 0xffff0000, v70
	v_lshlrev_b32_e32 v198, 16, v71
	v_and_b32_e32 v199, 0xffff0000, v71
	v_pk_add_f32 v[184:185], v[184:185], v[192:193]
	v_pk_add_f32 v[186:187], v[186:187], v[194:195]
	v_pk_add_f32 v[188:189], v[188:189], v[196:197]
	v_pk_add_f32 v[190:191], v[190:191], v[198:199]
	s_mov_b64 exec, s[26:27]
	v_pk_fma_f32 v[184:185], v[184:185], v[174:175], v[176:177] op_sel_hi:[1,0,1] neg_lo:[0,0,1] neg_hi:[0,0,1]
	v_pk_fma_f32 v[186:187], v[186:187], v[174:175], v[178:179] op_sel_hi:[1,0,1] neg_lo:[0,0,1] neg_hi:[0,0,1]
	v_pk_fma_f32 v[188:189], v[188:189], v[174:175], v[180:181] op_sel_hi:[1,0,1] neg_lo:[0,0,1] neg_hi:[0,0,1]
	v_pk_fma_f32 v[190:191], v[190:191], v[174:175], v[182:183] op_sel_hi:[1,0,1] neg_lo:[0,0,1] neg_hi:[0,0,1]
	v_cvt_pk_bf16_f32 v200, v184, v185
	v_cvt_pk_bf16_f32 v201, v186, v187
	v_cvt_pk_bf16_f32 v202, v188, v189
	v_cvt_pk_bf16_f32 v203, v190, v191
	s_add_i32 s21, s20, 6
	s_lshl_b32 s21, s21, 10
	s_add_u32 s24, s88, s21
	s_addc_u32 s25, s89, 0
	global_store_dwordx4 v175, v[200:203], s[24:25]
	s_add_i32 s21, s22, 8
	v_min_u32_e32 v173, s21, v204
	v_cvt_f32_u32_e32 v0, v173
	v_div_scale_f32 v1, s[0:1], v0, v0, 1.0
	v_rcp_f32_e32 v2, v1
	v_div_scale_f32 v3, vcc, 1.0, v0, 1.0
	v_fma_f32 v4, -v1, v2, 1.0
	v_fmac_f32_e32 v2, v4, v2
	v_mul_f32_e32 v4, v3, v2
	v_fma_f32 v5, -v1, v4, v3
	v_fmac_f32_e32 v4, v5, v2
	v_fma_f32 v1, -v1, v4, v3
	v_div_fmas_f32 v1, v1, v2, v4
	v_div_fixup_f32 v174, v1, v0, 1.0
	s_waitcnt vmcnt(7)
	v_lshlrev_b32_e32 v176, 16, v132
	v_and_b32_e32 v177, 0xffff0000, v132
	v_lshlrev_b32_e32 v178, 16, v133
	v_and_b32_e32 v179, 0xffff0000, v133
	v_lshlrev_b32_e32 v180, 16, v134
	v_and_b32_e32 v181, 0xffff0000, v134
	v_lshlrev_b32_e32 v182, 16, v135
	v_and_b32_e32 v183, 0xffff0000, v135
	v_mov_b32_e32 v184, v176
	v_mov_b32_e32 v185, v177
	v_mov_b32_e32 v186, v178
	v_mov_b32_e32 v187, v179
	v_mov_b32_e32 v188, v180
	v_mov_b32_e32 v189, v181
	v_mov_b32_e32 v190, v182
	v_mov_b32_e32 v191, v183
	v_cmp_lt_u32_e32 vcc, 1, v173
	s_and_b64 exec, exec, vcc
	v_lshlrev_b32_e32 v192, 16, v128
	v_and_b32_e32 v193, 0xffff0000, v128
	v_lshlrev_b32_e32 v194, 16, v129
	v_and_b32_e32 v195, 0xffff0000, v129
	v_lshlrev_b32_e32 v196, 16, v130
	v_and_b32_e32 v197, 0xffff0000, v130
	v_lshlrev_b32_e32 v198, 16, v131
	v_and_b32_e32 v199, 0xffff0000, v131
	v_pk_add_f32 v[184:185], v[184:185], v[192:193]
	v_pk_add_f32 v[186:187], v[186:187], v[194:195]
	v_pk_add_f32 v[188:189], v[188:189], v[196:197]
	v_pk_add_f32 v[190:191], v[190:191], v[198:199]
	v_cmp_lt_u32_e32 vcc, 2, v173
	s_and_b64 exec, exec, vcc
	v_lshlrev_b32_e32 v192, 16, v124
	v_and_b32_e32 v193, 0xffff0000, v124
	v_lshlrev_b32_e32 v194, 16, v125
	v_and_b32_e32 v195, 0xffff0000, v125
	v_lshlrev_b32_e32 v196, 16, v126
	v_and_b32_e32 v197, 0xffff0000, v126
	v_lshlrev_b32_e32 v198, 16, v127
	v_and_b32_e32 v199, 0xffff0000, v127
	v_pk_add_f32 v[184:185], v[184:185], v[192:193]
	v_pk_add_f32 v[186:187], v[186:187], v[194:195]
	v_pk_add_f32 v[188:189], v[188:189], v[196:197]
	v_pk_add_f32 v[190:191], v[190:191], v[198:199]
	v_cmp_lt_u32_e32 vcc, 3, v173
	s_and_b64 exec, exec, vcc
	v_lshlrev_b32_e32 v192, 16, v120
	v_and_b32_e32 v193, 0xffff0000, v120
	v_lshlrev_b32_e32 v194, 16, v121
	v_and_b32_e32 v195, 0xffff0000, v121
	v_lshlrev_b32_e32 v196, 16, v122
	v_and_b32_e32 v197, 0xffff0000, v122
	v_lshlrev_b32_e32 v198, 16, v123
	v_and_b32_e32 v199, 0xffff0000, v123
	v_pk_add_f32 v[184:185], v[184:185], v[192:193]
	v_pk_add_f32 v[186:187], v[186:187], v[194:195]
	v_pk_add_f32 v[188:189], v[188:189], v[196:197]
	v_pk_add_f32 v[190:191], v[190:191], v[198:199]
	v_cmp_lt_u32_e32 vcc, 4, v173
	s_and_b64 exec, exec, vcc
	v_lshlrev_b32_e32 v192, 16, v116
	v_and_b32_e32 v193, 0xffff0000, v116
	v_lshlrev_b32_e32 v194, 16, v117
	v_and_b32_e32 v195, 0xffff0000, v117
	v_lshlrev_b32_e32 v196, 16, v118
	v_and_b32_e32 v197, 0xffff0000, v118
	v_lshlrev_b32_e32 v198, 16, v119
	v_and_b32_e32 v199, 0xffff0000, v119
	v_pk_add_f32 v[184:185], v[184:185], v[192:193]
	v_pk_add_f32 v[186:187], v[186:187], v[194:195]
	v_pk_add_f32 v[188:189], v[188:189], v[196:197]
	v_pk_add_f32 v[190:191], v[190:191], v[198:199]
	v_cmp_lt_u32_e32 vcc, 5, v173
	s_and_b64 exec, exec, vcc
	v_lshlrev_b32_e32 v192, 16, v112
	v_and_b32_e32 v193, 0xffff0000, v112
	v_lshlrev_b32_e32 v194, 16, v113
	v_and_b32_e32 v195, 0xffff0000, v113
	v_lshlrev_b32_e32 v196, 16, v114
	v_and_b32_e32 v197, 0xffff0000, v114
	v_lshlrev_b32_e32 v198, 16, v115
	v_and_b32_e32 v199, 0xffff0000, v115
	v_pk_add_f32 v[184:185], v[184:185], v[192:193]
	v_pk_add_f32 v[186:187], v[186:187], v[194:195]
	v_pk_add_f32 v[188:189], v[188:189], v[196:197]
	v_pk_add_f32 v[190:191], v[190:191], v[198:199]
	v_cmp_lt_u32_e32 vcc, 6, v173
	s_and_b64 exec, exec, vcc
	v_lshlrev_b32_e32 v192, 16, v108
	v_and_b32_e32 v193, 0xffff0000, v108
	v_lshlrev_b32_e32 v194, 16, v109
	v_and_b32_e32 v195, 0xffff0000, v109
	v_lshlrev_b32_e32 v196, 16, v110
	v_and_b32_e32 v197, 0xffff0000, v110
	v_lshlrev_b32_e32 v198, 16, v111
	v_and_b32_e32 v199, 0xffff0000, v111
	v_pk_add_f32 v[184:185], v[184:185], v[192:193]
	v_pk_add_f32 v[186:187], v[186:187], v[194:195]
	v_pk_add_f32 v[188:189], v[188:189], v[196:197]
	v_pk_add_f32 v[190:191], v[190:191], v[198:199]
	v_cmp_lt_u32_e32 vcc, 7, v173
	s_and_b64 exec, exec, vcc
	v_lshlrev_b32_e32 v192, 16, v104
	v_and_b32_e32 v193, 0xffff0000, v104
	v_lshlrev_b32_e32 v194, 16, v105
	v_and_b32_e32 v195, 0xffff0000, v105
	v_lshlrev_b32_e32 v196, 16, v106
	v_and_b32_e32 v197, 0xffff0000, v106
	v_lshlrev_b32_e32 v198, 16, v107
	v_and_b32_e32 v199, 0xffff0000, v107
	v_pk_add_f32 v[184:185], v[184:185], v[192:193]
	v_pk_add_f32 v[186:187], v[186:187], v[194:195]
	v_pk_add_f32 v[188:189], v[188:189], v[196:197]
	v_pk_add_f32 v[190:191], v[190:191], v[198:199]
	v_cmp_lt_u32_e32 vcc, 8, v173
	s_and_b64 exec, exec, vcc
	v_lshlrev_b32_e32 v192, 16, v100
	v_and_b32_e32 v193, 0xffff0000, v100
	v_lshlrev_b32_e32 v194, 16, v101
	v_and_b32_e32 v195, 0xffff0000, v101
	v_lshlrev_b32_e32 v196, 16, v102
	v_and_b32_e32 v197, 0xffff0000, v102
	v_lshlrev_b32_e32 v198, 16, v103
	v_and_b32_e32 v199, 0xffff0000, v103
	v_pk_add_f32 v[184:185], v[184:185], v[192:193]
	v_pk_add_f32 v[186:187], v[186:187], v[194:195]
	v_pk_add_f32 v[188:189], v[188:189], v[196:197]
	v_pk_add_f32 v[190:191], v[190:191], v[198:199]
	v_cmp_lt_u32_e32 vcc, 9, v173
	s_and_b64 exec, exec, vcc
	v_lshlrev_b32_e32 v192, 16, v96
	v_and_b32_e32 v193, 0xffff0000, v96
	v_lshlrev_b32_e32 v194, 16, v97
	v_and_b32_e32 v195, 0xffff0000, v97
	v_lshlrev_b32_e32 v196, 16, v98
	v_and_b32_e32 v197, 0xffff0000, v98
	v_lshlrev_b32_e32 v198, 16, v99
	v_and_b32_e32 v199, 0xffff0000, v99
	v_pk_add_f32 v[184:185], v[184:185], v[192:193]
	v_pk_add_f32 v[186:187], v[186:187], v[194:195]
	v_pk_add_f32 v[188:189], v[188:189], v[196:197]
	v_pk_add_f32 v[190:191], v[190:191], v[198:199]
	v_cmp_lt_u32_e32 vcc, 10, v173
	s_and_b64 exec, exec, vcc
	v_lshlrev_b32_e32 v192, 16, v92
	v_and_b32_e32 v193, 0xffff0000, v92
	v_lshlrev_b32_e32 v194, 16, v93
	v_and_b32_e32 v195, 0xffff0000, v93
	v_lshlrev_b32_e32 v196, 16, v94
	v_and_b32_e32 v197, 0xffff0000, v94
	v_lshlrev_b32_e32 v198, 16, v95
	v_and_b32_e32 v199, 0xffff0000, v95
	v_pk_add_f32 v[184:185], v[184:185], v[192:193]
	v_pk_add_f32 v[186:187], v[186:187], v[194:195]
	v_pk_add_f32 v[188:189], v[188:189], v[196:197]
	v_pk_add_f32 v[190:191], v[190:191], v[198:199]
	v_cmp_lt_u32_e32 vcc, 11, v173
	s_and_b64 exec, exec, vcc
	v_lshlrev_b32_e32 v192, 16, v88
	v_and_b32_e32 v193, 0xffff0000, v88
	v_lshlrev_b32_e32 v194, 16, v89
	v_and_b32_e32 v195, 0xffff0000, v89
	v_lshlrev_b32_e32 v196, 16, v90
	v_and_b32_e32 v197, 0xffff0000, v90
	v_lshlrev_b32_e32 v198, 16, v91
	v_and_b32_e32 v199, 0xffff0000, v91
	v_pk_add_f32 v[184:185], v[184:185], v[192:193]
	v_pk_add_f32 v[186:187], v[186:187], v[194:195]
	v_pk_add_f32 v[188:189], v[188:189], v[196:197]
	v_pk_add_f32 v[190:191], v[190:191], v[198:199]
	v_cmp_lt_u32_e32 vcc, 12, v173
	s_and_b64 exec, exec, vcc
	v_lshlrev_b32_e32 v192, 16, v84
	v_and_b32_e32 v193, 0xffff0000, v84
	v_lshlrev_b32_e32 v194, 16, v85
	v_and_b32_e32 v195, 0xffff0000, v85
	v_lshlrev_b32_e32 v196, 16, v86
	v_and_b32_e32 v197, 0xffff0000, v86
	v_lshlrev_b32_e32 v198, 16, v87
	v_and_b32_e32 v199, 0xffff0000, v87
	v_pk_add_f32 v[184:185], v[184:185], v[192:193]
	v_pk_add_f32 v[186:187], v[186:187], v[194:195]
	v_pk_add_f32 v[188:189], v[188:189], v[196:197]
	v_pk_add_f32 v[190:191], v[190:191], v[198:199]
	v_cmp_lt_u32_e32 vcc, 13, v173
	s_and_b64 exec, exec, vcc
	v_lshlrev_b32_e32 v192, 16, v80
	v_and_b32_e32 v193, 0xffff0000, v80
	v_lshlrev_b32_e32 v194, 16, v81
	v_and_b32_e32 v195, 0xffff0000, v81
	v_lshlrev_b32_e32 v196, 16, v82
	v_and_b32_e32 v197, 0xffff0000, v82
	v_lshlrev_b32_e32 v198, 16, v83
	v_and_b32_e32 v199, 0xffff0000, v83
	v_pk_add_f32 v[184:185], v[184:185], v[192:193]
	v_pk_add_f32 v[186:187], v[186:187], v[194:195]
	v_pk_add_f32 v[188:189], v[188:189], v[196:197]
	v_pk_add_f32 v[190:191], v[190:191], v[198:199]
	v_cmp_lt_u32_e32 vcc, 14, v173
	s_and_b64 exec, exec, vcc
	v_lshlrev_b32_e32 v192, 16, v76
	v_and_b32_e32 v193, 0xffff0000, v76
	v_lshlrev_b32_e32 v194, 16, v77
	v_and_b32_e32 v195, 0xffff0000, v77
	v_lshlrev_b32_e32 v196, 16, v78
	v_and_b32_e32 v197, 0xffff0000, v78
	v_lshlrev_b32_e32 v198, 16, v79
	v_and_b32_e32 v199, 0xffff0000, v79
	v_pk_add_f32 v[184:185], v[184:185], v[192:193]
	v_pk_add_f32 v[186:187], v[186:187], v[194:195]
	v_pk_add_f32 v[188:189], v[188:189], v[196:197]
	v_pk_add_f32 v[190:191], v[190:191], v[198:199]
	v_cmp_lt_u32_e32 vcc, 15, v173
	s_and_b64 exec, exec, vcc
	v_lshlrev_b32_e32 v192, 16, v72
	v_and_b32_e32 v193, 0xffff0000, v72
	v_lshlrev_b32_e32 v194, 16, v73
	v_and_b32_e32 v195, 0xffff0000, v73
	v_lshlrev_b32_e32 v196, 16, v74
	v_and_b32_e32 v197, 0xffff0000, v74
	v_lshlrev_b32_e32 v198, 16, v75
	v_and_b32_e32 v199, 0xffff0000, v75
	v_pk_add_f32 v[184:185], v[184:185], v[192:193]
	v_pk_add_f32 v[186:187], v[186:187], v[194:195]
	v_pk_add_f32 v[188:189], v[188:189], v[196:197]
	v_pk_add_f32 v[190:191], v[190:191], v[198:199]
	s_mov_b64 exec, s[26:27]
	v_pk_fma_f32 v[184:185], v[184:185], v[174:175], v[176:177] op_sel_hi:[1,0,1] neg_lo:[0,0,1] neg_hi:[0,0,1]
	v_pk_fma_f32 v[186:187], v[186:187], v[174:175], v[178:179] op_sel_hi:[1,0,1] neg_lo:[0,0,1] neg_hi:[0,0,1]
	v_pk_fma_f32 v[188:189], v[188:189], v[174:175], v[180:181] op_sel_hi:[1,0,1] neg_lo:[0,0,1] neg_hi:[0,0,1]
	v_pk_fma_f32 v[190:191], v[190:191], v[174:175], v[182:183] op_sel_hi:[1,0,1] neg_lo:[0,0,1] neg_hi:[0,0,1]
	v_cvt_pk_bf16_f32 v200, v184, v185
	v_cvt_pk_bf16_f32 v201, v186, v187
	v_cvt_pk_bf16_f32 v202, v188, v189
	v_cvt_pk_bf16_f32 v203, v190, v191
	s_add_i32 s21, s20, 7
	s_lshl_b32 s21, s21, 10
	s_add_u32 s24, s88, s21
	s_addc_u32 s25, s89, 0
	global_store_dwordx4 v175, v[200:203], s[24:25]
	s_cmpk_lt_i32 s2, 0x180
	s_cbranch_scc1 .LBB0_271
	s_sub_i32 s28, 0x1ff, s2
	s_lshl_b32 s20, s28, 2
	s_add_i32 s20, s20, s23
	s_add_i32 s20, s20, 0x4000
	s_mul_i32 s28, s28, 15
	s_add_i32 s28, s28, s23
	s_add_i32 s28, s28, 15
	v_add_u32_e32 v173, 0xfffff200, v172
	v_lshlrev_b32_e32 v173, 1, v173
	v_and_b32_e32 v174, 63, v218
	v_lshrrev_b32_e32 v174, 4, v174
	s_mul_i32 s21, s20, 0x1200
	s_add_u32 s24, s90, s21
	s_addc_u32 s25, s91, 0
	global_load_dwordx4 v[164:167], v172, s[24:25]
	s_cmp_ge_i32 s23, 1
	s_cbranch_scc1 .Lps_lz1
	s_sub_i32 s21, s28, 1
	s_lshl_b32 s21, s21, 11
	s_add_u32 s24, s72, s21
	s_addc_u32 s25, s73, 0
	global_load_dwordx4 v[44:47], v173, s[24:25]
	global_load_dwordx4 v[48:51], v173, s[24:25] offset:16
	s_branch .Lps_ld1
